# nt also on last-use residual-base loads (x, XB1, XB2) in P3/P7/P9 epilogues and on the final output stores
# speedup vs baseline: 1.0442x; 1.0108x over previous
;     __device__ __forceinline__ void operator()(const f32x4 (&acc)[2][2][4][2], const Unit& u, int wr, int wc, int fr, int fq) const {
;         const float* g = gate + (u.pm >> 5) * 9216;
;         const int row0 = u.pm * BM + wr * 64 + fr, col0 = u.pn * BM + wc * 32 + 8 * fq;
;         f32x4 gv[2][2];
; #pragma unroll
;         for (int bj = 0; bj < 2; ++bj)
; #pragma unroll
;             for (int n = 0; n < 2; ++n) gv[bj][n] = *(const f32x4*)(g + col0 + bj * HALF + 4 * n) * coef;
; #pragma unroll
;         for (int ai = 0; ai < 2; ++ai)
; #pragma unroll
;             for (int m = 0; m < 4; ++m) {
;                 const int row = row0 + ai * HALF + m * 16; const size_t off = (size_t)row * 1024 + col0;
;                 f32x4 b0[2], b1[2];
; #pragma unroll
;                 for (int bj = 0; bj < 2; ++bj) {
;                     if (BASE_BF16) { const u32x4 t = *(const u32x4*)((const bf16_t*)base + off + bj * HALF);
;                         b0[bj] = (f32x4){bf_lo(t.x), bf_hi(t.x), bf_lo(t.y), bf_hi(t.y)}; b1[bj] = (f32x4){bf_lo(t.z), bf_hi(t.z), bf_lo(t.w), bf_hi(t.w)}; }
;                     else { b0[bj] = *(const f32x4*)((const float*)base + off + bj * HALF); b1[bj] = *(const f32x4*)((const float*)base + off + bj * HALF + 4); }
;                 }
;                 float ss = 0.f;
; #pragma unroll
;                 for (int bj = 0; bj < 2; ++bj) {
;                     const f32x4 v0 = b0[bj] + gv[bj][0] * acc[ai][bj][m][0], v1 = b1[bj] + gv[bj][1] * acc[ai][bj][m][1];
;                     if (OUT_BF16) {
;                         u32x4 w; w.x = cvt_pk_bf16(v0[0], v0[1]); w.y = cvt_pk_bf16(v0[2], v0[3]); w.z = cvt_pk_bf16(v1[0], v1[1]); w.w = cvt_pk_bf16(v1[2], v1[3]);
;                         *(u32x4*)((bf16_t*)out + off + bj * HALF) = w;
;                         ss += ((v0[0] * v0[0] + v0[1] * v0[1]) + (v0[2] * v0[2] + v0[3] * v0[3])) + ((v1[0] * v1[0] + v1[1] * v1[1]) + (v1[2] * v1[2] + v1[3] * v1[3]));
;                     } else { *(f32x4*)((float*)out + off + bj * HALF) = v0; *(f32x4*)((float*)out + off + bj * HALF + 4) = v1; }
;                 }
;                 if (OUT_BF16) { ss += __shfl_xor(ss, 16); ss += __shfl_xor(ss, 32); if (fq == 0) rowp[(size_t)row * 16 + u.pn * 4 + wc] = ss; }
;             }
.LBB0_292:
	s_lshr_b32 s22, s65, 5
	s_mulk_i32 s22, 0x2400
	s_ashr_i32 s23, s22, 31
	s_lshl_b64 s[22:23], s[22:23], 2
	s_add_u32 s22, s44, s22
	v_lshl_or_b32 v144, s12, 8, v167
	s_addc_u32 s23, s45, s23
	v_ashrrev_i32_e32 v145, 31, v144
	v_lshl_add_u64 v[154:155], v[144:145], 2, s[22:23]
	global_load_dwordx4 v[146:149], v[154:155], off offset:16 nt
	global_load_dwordx4 v[150:153], v[154:155], off nt
	global_load_dwordx4 v[174:177], v[154:155], off offset:528 nt
	global_load_dwordx4 v[178:181], v[154:155], off offset:512 nt
	v_lshl_add_u32 v154, s65, 8, v161
	v_ashrrev_i32_e32 v155, 31, v154
	v_lshlrev_b64 v[156:157], 10, v[154:155]
	v_lshl_add_u64 v[198:199], v[156:157], 0, v[144:145]
	v_lshl_add_u64 v[156:157], v[198:199], 2, s[60:61]
	global_load_dwordx4 v[182:185], v[156:157], off nt
	global_load_dwordx4 v[186:189], v[156:157], off offset:16 nt
	global_load_dwordx4 v[190:193], v[156:157], off offset:512 nt
	global_load_dwordx4 v[194:197], v[156:157], off offset:528 nt
	v_and_b32_e32 v157, 64, v171
	v_xor_b32_e32 v156, 16, v171
	v_add_u32_e32 v157, 64, v157
	v_xor_b32_e32 v158, 32, v171
	v_cmp_lt_i32_e32 vcc, v156, v157
	s_lshl_b32 s22, s12, 2
	s_ashr_i32 s23, s22, 31
	v_cndmask_b32_e32 v156, v171, v156, vcc
	v_cmp_lt_i32_e32 vcc, v158, v157
	v_lshlrev_b32_e32 v173, 2, v156
	s_waitcnt vmcnt(0)
	v_pk_mul_f32 v[162:163], v[152:153], 0.5 op_sel_hi:[1,0]
	v_cndmask_b32_e32 v157, v171, v158, vcc
	v_lshlrev_b32_e32 v172, 2, v157
	v_pk_mul_f32 v[164:165], v[150:151], 0.5 op_sel_hi:[1,0]
	v_pk_mul_f32 v[156:157], v[148:149], 0.5 op_sel_hi:[1,0]
	v_pk_mul_f32 v[158:159], v[146:147], 0.5 op_sel_hi:[1,0]
	v_pk_mul_f32 v[150:151], v[180:181], 0.5 op_sel_hi:[1,0]
	v_pk_mul_f32 v[152:153], v[178:179], 0.5 op_sel_hi:[1,0]
	v_pk_mul_f32 v[146:147], v[176:177], 0.5 op_sel_hi:[1,0]
	v_pk_mul_f32 v[148:149], v[174:175], 0.5 op_sel_hi:[1,0]
	v_pk_fma_f32 v[126:127], v[126:127], v[162:163], v[184:185]
	v_pk_fma_f32 v[124:125], v[124:125], v[164:165], v[182:183]
	v_pk_fma_f32 v[122:123], v[122:123], v[156:157], v[188:189]
	v_pk_fma_f32 v[120:121], v[120:121], v[158:159], v[186:187]
	v_pk_fma_f32 v[118:119], v[118:119], v[150:151], v[192:193]
	v_pk_fma_f32 v[116:117], v[116:117], v[152:153], v[190:191]
	v_pk_fma_f32 v[174:175], v[114:115], v[146:147], v[196:197]
	v_pk_fma_f32 v[176:177], v[112:113], v[148:149], v[194:195]
	v_cvt_pk_bf16_f32 v112, v124, v125
	v_cvt_pk_bf16_f32 v113, v126, v127
	v_cvt_pk_bf16_f32 v114, v120, v121
	v_mul_f32_e32 v115, v125, v125
	v_mul_f32_e32 v125, v127, v127
	v_mul_f32_e32 v121, v121, v121
	v_mul_f32_e32 v127, v123, v123
	v_mul_f32_e32 v178, v117, v117
	v_mul_f32_e32 v179, v119, v119
	v_mul_f32_e32 v180, v177, v177
	v_mul_f32_e32 v181, v175, v175
	v_fmac_f32_e32 v115, v124, v124
	v_fmac_f32_e32 v125, v126, v126
	v_fmac_f32_e32 v121, v120, v120
	v_fmac_f32_e32 v127, v122, v122
	v_fmac_f32_e32 v178, v116, v116
	v_fmac_f32_e32 v179, v118, v118
	v_fmac_f32_e32 v180, v176, v176
	v_fmac_f32_e32 v181, v174, v174
	v_add_f32_e32 v115, v115, v125
	v_add_f32_e32 v120, v121, v127
	v_add_f32_e32 v121, v178, v179
	v_add_f32_e32 v124, v180, v181
	v_add_f32_e32 v115, v115, v120
	v_add_f32_e32 v120, v121, v124
	v_add_f32_e32 v124, v115, v120
	ds_bpermute_b32 v125, v173, v124
	v_cvt_pk_bf16_f32 v115, v122, v123
	v_lshl_add_u64 v[120:121], v[198:199], 1, s[84:85]
	global_store_dwordx4 v[120:121], v[112:115], off
	s_waitcnt lgkmcnt(0)
	s_nop 0
	v_add_f32_e32 v112, v124, v125
	ds_bpermute_b32 v113, v172, v112
	v_cvt_pk_bf16_f32 v114, v116, v117
	v_cvt_pk_bf16_f32 v115, v118, v119
	v_cvt_pk_bf16_f32 v116, v176, v177
	v_cvt_pk_bf16_f32 v117, v174, v175
	global_store_dwordx4 v[120:121], v[114:117], off offset:256
	s_and_saveexec_b64 s[34:35], s[4:5]
	s_cbranch_execz .LBB0_294
	s_waitcnt lgkmcnt(0)
	v_add_f32_e32 v114, v112, v113
	v_lshlrev_b64 v[112:113], 6, v[154:155]
	v_lshl_add_u64 v[112:113], s[8:9], 0, v[112:113]
	v_lshl_add_u64 v[112:113], s[22:23], 2, v[112:113]
	s_lshl_b32 s12, s52, 2
	v_lshl_add_u64 v[112:113], v[112:113], 0, s[12:13]
	global_store_dword v[112:113], v114, off
.LBB0_294:
	s_or_b64 exec, exec, s[34:35]
	v_or_b32_e32 v112, 16, v154
	s_waitcnt lgkmcnt(0)
	v_ashrrev_i32_e32 v113, 31, v112
	v_lshlrev_b64 v[114:115], 10, v[112:113]
	v_lshl_add_u64 v[126:127], v[114:115], 0, v[144:145]
	v_lshl_add_u64 v[174:175], v[126:127], 2, s[60:61]
	global_load_dwordx4 v[114:117], v[174:175], off nt
	global_load_dwordx4 v[118:121], v[174:175], off offset:16 nt
	global_load_dwordx4 v[122:125], v[174:175], off offset:512 nt
	s_nop 0
	global_load_dwordx4 v[174:177], v[174:175], off offset:528 nt
	s_waitcnt vmcnt(3)
	v_pk_fma_f32 v[110:111], v[110:111], v[162:163], v[116:117]
	v_pk_fma_f32 v[108:109], v[108:109], v[164:165], v[114:115]
	s_waitcnt vmcnt(2)
	v_pk_fma_f32 v[106:107], v[106:107], v[156:157], v[120:121]
	v_pk_fma_f32 v[104:105], v[104:105], v[158:159], v[118:119]
	s_waitcnt vmcnt(1)
	v_pk_fma_f32 v[102:103], v[102:103], v[150:151], v[124:125]
	v_pk_fma_f32 v[100:101], v[100:101], v[152:153], v[122:123]
	s_waitcnt vmcnt(0)
	v_pk_fma_f32 v[114:115], v[98:99], v[146:147], v[176:177]
	v_pk_fma_f32 v[116:117], v[96:97], v[148:149], v[174:175]
	v_cvt_pk_bf16_f32 v96, v108, v109
	v_cvt_pk_bf16_f32 v97, v110, v111
	v_cvt_pk_bf16_f32 v98, v104, v105
	v_mul_f32_e32 v99, v109, v109
	v_mul_f32_e32 v109, v111, v111
	v_mul_f32_e32 v105, v105, v105
	v_mul_f32_e32 v111, v107, v107
	v_mul_f32_e32 v118, v101, v101
	v_mul_f32_e32 v119, v103, v103
	v_mul_f32_e32 v120, v117, v117
	v_mul_f32_e32 v121, v115, v115
	v_fmac_f32_e32 v99, v108, v108
	v_fmac_f32_e32 v109, v110, v110
	v_fmac_f32_e32 v105, v104, v104
	v_fmac_f32_e32 v111, v106, v106
	v_fmac_f32_e32 v118, v100, v100
	v_fmac_f32_e32 v119, v102, v102
	v_fmac_f32_e32 v120, v116, v116
	v_fmac_f32_e32 v121, v114, v114
	v_add_f32_e32 v99, v99, v109
	v_add_f32_e32 v104, v105, v111
	v_add_f32_e32 v105, v118, v119
	v_add_f32_e32 v108, v120, v121
	v_add_f32_e32 v99, v99, v104
	v_add_f32_e32 v104, v105, v108
	v_add_f32_e32 v108, v99, v104
	ds_bpermute_b32 v109, v173, v108
	v_cvt_pk_bf16_f32 v99, v106, v107
	v_lshl_add_u64 v[104:105], v[126:127], 1, s[84:85]
	global_store_dwordx4 v[104:105], v[96:99], off
	s_waitcnt lgkmcnt(0)
	s_nop 0
	v_add_f32_e32 v96, v108, v109
	ds_bpermute_b32 v97, v172, v96
	v_cvt_pk_bf16_f32 v98, v100, v101
	v_cvt_pk_bf16_f32 v99, v102, v103
	v_cvt_pk_bf16_f32 v100, v116, v117
	v_cvt_pk_bf16_f32 v101, v114, v115
	global_store_dwordx4 v[104:105], v[98:101], off offset:256
	s_and_saveexec_b64 s[34:35], s[4:5]
	s_cbranch_execz .LBB0_296
	s_waitcnt lgkmcnt(0)
	v_add_f32_e32 v98, v96, v97
	v_lshlrev_b64 v[96:97], 6, v[112:113]
	v_lshl_add_u64 v[96:97], s[8:9], 0, v[96:97]
	v_lshl_add_u64 v[96:97], s[22:23], 2, v[96:97]
	s_lshl_b32 s12, s52, 2
	v_lshl_add_u64 v[96:97], v[96:97], 0, s[12:13]
	global_store_dword v[96:97], v98, off
; __device__ __forceinline__ unsigned cvt_pk_bf16(float lo, float hi) { f32x2_cv v = {lo, hi}; bf16x2_cv b = __builtin_convertvector(v, bf16x2_cv); return __builtin_bit_cast(unsigned, b); }
;     __device__ __forceinline__ void operator()(const f32x4 (&acc)[2][2][4][2], const Unit& u, int wr, int wc, int fr, int fq) const {
;     ...
;         for (int ai = 0; ai < 2; ++ai)
; #pragma unroll
;             for (int m = 0; m < 4; ++m) {
;                 const int row = row0 + ai * HALF + m * 16; const size_t off = (size_t)row * 1024 + col0;
;                 f32x4 b0[2], b1[2];
; #pragma unroll
;                 for (int bj = 0; bj < 2; ++bj) {
;                     if (BASE_BF16) { const u32x4 t = *(const u32x4*)((const bf16_t*)base + off + bj * HALF);
;                         b0[bj] = (f32x4){bf_lo(t.x), bf_hi(t.x), bf_lo(t.y), bf_hi(t.y)}; b1[bj] = (f32x4){bf_lo(t.z), bf_hi(t.z), bf_lo(t.w), bf_hi(t.w)}; }
;                     else { b0[bj] = *(const f32x4*)((const float*)base + off + bj * HALF); b1[bj] = *(const f32x4*)((const float*)base + off + bj * HALF + 4); }
;                 }
;                 float ss = 0.f;
; #pragma unroll
;                 for (int bj = 0; bj < 2; ++bj) {
;                     const f32x4 v0 = b0[bj] + gv[bj][0] * acc[ai][bj][m][0], v1 = b1[bj] + gv[bj][1] * acc[ai][bj][m][1];
;                     if (OUT_BF16) {
;                         u32x4 w; w.x = cvt_pk_bf16(v0[0], v0[1]); w.y = cvt_pk_bf16(v0[2], v0[3]); w.z = cvt_pk_bf16(v1[0], v1[1]); w.w = cvt_pk_bf16(v1[2], v1[3]);
;                         *(u32x4*)((bf16_t*)out + off + bj * HALF) = w;
;                         ss += ((v0[0] * v0[0] + v0[1] * v0[1]) + (v0[2] * v0[2] + v0[3] * v0[3])) + ((v1[0] * v1[0] + v1[1] * v1[1]) + (v1[2] * v1[2] + v1[3] * v1[3]));
;                     } else { *(f32x4*)((float*)out + off + bj * HALF) = v0; *(f32x4*)((float*)out + off + bj * HALF + 4) = v1; }
;                 }
;                 if (OUT_BF16) { ss += __shfl_xor(ss, 16); ss += __shfl_xor(ss, 32); if (fq == 0) rowp[(size_t)row * 16 + u.pn * 4 + wc] = ss; }
;             }
.LBB0_296:
	s_or_b64 exec, exec, s[34:35]
	v_or_b32_e32 v96, 32, v154
	s_waitcnt lgkmcnt(0)
	v_ashrrev_i32_e32 v97, 31, v96
	v_lshlrev_b64 v[98:99], 10, v[96:97]
	v_lshl_add_u64 v[114:115], v[98:99], 0, v[144:145]
	v_lshl_add_u64 v[110:111], v[114:115], 2, s[60:61]
	global_load_dwordx4 v[98:101], v[110:111], off nt
	global_load_dwordx4 v[102:105], v[110:111], off offset:16 nt
	global_load_dwordx4 v[106:109], v[110:111], off offset:512 nt
	s_nop 0
	global_load_dwordx4 v[110:113], v[110:111], off offset:528 nt
	s_waitcnt vmcnt(3)
	v_pk_fma_f32 v[94:95], v[94:95], v[162:163], v[100:101]
	v_pk_fma_f32 v[92:93], v[92:93], v[164:165], v[98:99]
	s_waitcnt vmcnt(2)
	v_pk_fma_f32 v[90:91], v[90:91], v[156:157], v[104:105]
	v_pk_fma_f32 v[88:89], v[88:89], v[158:159], v[102:103]
	s_waitcnt vmcnt(1)
	v_pk_fma_f32 v[86:87], v[86:87], v[150:151], v[108:109]
	v_pk_fma_f32 v[84:85], v[84:85], v[152:153], v[106:107]
	s_waitcnt vmcnt(0)
	v_pk_fma_f32 v[98:99], v[82:83], v[146:147], v[112:113]
	v_pk_fma_f32 v[100:101], v[80:81], v[148:149], v[110:111]
	v_cvt_pk_bf16_f32 v80, v92, v93
	v_cvt_pk_bf16_f32 v81, v94, v95
	v_cvt_pk_bf16_f32 v82, v88, v89
	v_mul_f32_e32 v83, v93, v93
	v_mul_f32_e32 v93, v95, v95
	v_mul_f32_e32 v89, v89, v89
	v_mul_f32_e32 v95, v91, v91
	v_mul_f32_e32 v102, v85, v85
	v_mul_f32_e32 v103, v87, v87
	v_mul_f32_e32 v104, v101, v101
	v_mul_f32_e32 v105, v99, v99
	v_fmac_f32_e32 v83, v92, v92
	v_fmac_f32_e32 v93, v94, v94
	v_fmac_f32_e32 v89, v88, v88
	v_fmac_f32_e32 v95, v90, v90
	v_fmac_f32_e32 v102, v84, v84
	v_fmac_f32_e32 v103, v86, v86
	v_fmac_f32_e32 v104, v100, v100
	v_fmac_f32_e32 v105, v98, v98
	v_add_f32_e32 v83, v83, v93
	v_add_f32_e32 v88, v89, v95
	v_add_f32_e32 v89, v102, v103
	v_add_f32_e32 v92, v104, v105
	v_add_f32_e32 v83, v83, v88
	v_add_f32_e32 v88, v89, v92
	v_add_f32_e32 v92, v83, v88
	ds_bpermute_b32 v93, v173, v92
	v_cvt_pk_bf16_f32 v83, v90, v91
	v_lshl_add_u64 v[88:89], v[114:115], 1, s[84:85]
	global_store_dwordx4 v[88:89], v[80:83], off
	s_waitcnt lgkmcnt(0)
	s_nop 0
	v_add_f32_e32 v80, v92, v93
	ds_bpermute_b32 v81, v172, v80
	v_cvt_pk_bf16_f32 v82, v84, v85
	v_cvt_pk_bf16_f32 v83, v86, v87
	v_cvt_pk_bf16_f32 v84, v100, v101
	v_cvt_pk_bf16_f32 v85, v98, v99
	global_store_dwordx4 v[88:89], v[82:85], off offset:256
	s_and_saveexec_b64 s[34:35], s[4:5]
	s_cbranch_execz .LBB0_298
	s_waitcnt lgkmcnt(0)
	v_add_f32_e32 v82, v80, v81
	v_lshlrev_b64 v[80:81], 6, v[96:97]
	v_lshl_add_u64 v[80:81], s[8:9], 0, v[80:81]
	v_lshl_add_u64 v[80:81], s[22:23], 2, v[80:81]
	s_lshl_b32 s12, s52, 2
	v_lshl_add_u64 v[80:81], v[80:81], 0, s[12:13]
	global_store_dword v[80:81], v82, off
.LBB0_298:
	s_or_b64 exec, exec, s[34:35]
	v_or_b32_e32 v80, 48, v154
	s_waitcnt lgkmcnt(0)
	v_ashrrev_i32_e32 v81, 31, v80
	v_lshlrev_b64 v[82:83], 10, v[80:81]
	v_lshl_add_u64 v[98:99], v[82:83], 0, v[144:145]
	v_lshl_add_u64 v[94:95], v[98:99], 2, s[60:61]
	global_load_dwordx4 v[82:85], v[94:95], off nt
	global_load_dwordx4 v[86:89], v[94:95], off offset:16 nt
	global_load_dwordx4 v[90:93], v[94:95], off offset:512 nt
	s_nop 0
	global_load_dwordx4 v[94:97], v[94:95], off offset:528 nt
	s_waitcnt vmcnt(3)
	v_pk_fma_f32 v[78:79], v[78:79], v[162:163], v[84:85]
	v_pk_fma_f32 v[76:77], v[76:77], v[164:165], v[82:83]
	s_waitcnt vmcnt(2)
	v_pk_fma_f32 v[74:75], v[74:75], v[156:157], v[88:89]
	v_pk_fma_f32 v[72:73], v[72:73], v[158:159], v[86:87]
	s_waitcnt vmcnt(1)
	v_pk_fma_f32 v[70:71], v[70:71], v[150:151], v[92:93]
	v_pk_fma_f32 v[68:69], v[68:69], v[152:153], v[90:91]
	s_waitcnt vmcnt(0)
	v_pk_fma_f32 v[82:83], v[66:67], v[146:147], v[96:97]
	v_pk_fma_f32 v[84:85], v[64:65], v[148:149], v[94:95]
	v_cvt_pk_bf16_f32 v64, v76, v77
	v_cvt_pk_bf16_f32 v65, v78, v79
	v_cvt_pk_bf16_f32 v66, v72, v73
	v_mul_f32_e32 v67, v77, v77
	v_mul_f32_e32 v77, v79, v79
	v_mul_f32_e32 v73, v73, v73
	v_mul_f32_e32 v79, v75, v75
	v_mul_f32_e32 v86, v69, v69
	v_mul_f32_e32 v87, v71, v71
	v_mul_f32_e32 v88, v85, v85
	v_mul_f32_e32 v89, v83, v83
	v_fmac_f32_e32 v67, v76, v76
	v_fmac_f32_e32 v77, v78, v78
	v_fmac_f32_e32 v73, v72, v72
	v_fmac_f32_e32 v79, v74, v74
	v_fmac_f32_e32 v86, v68, v68
	v_fmac_f32_e32 v87, v70, v70
	v_fmac_f32_e32 v88, v84, v84
	v_fmac_f32_e32 v89, v82, v82
	v_add_f32_e32 v67, v67, v77
	v_add_f32_e32 v72, v73, v79
	v_add_f32_e32 v73, v86, v87
	v_add_f32_e32 v76, v88, v89
	v_add_f32_e32 v67, v67, v72
	v_add_f32_e32 v72, v73, v76
	v_add_f32_e32 v76, v67, v72
	ds_bpermute_b32 v77, v173, v76
	v_cvt_pk_bf16_f32 v67, v74, v75
	v_lshl_add_u64 v[72:73], v[98:99], 1, s[84:85]
	global_store_dwordx4 v[72:73], v[64:67], off
	s_waitcnt lgkmcnt(0)
	s_nop 0
	v_add_f32_e32 v64, v76, v77
	ds_bpermute_b32 v65, v172, v64
	v_cvt_pk_bf16_f32 v66, v68, v69
	v_cvt_pk_bf16_f32 v67, v70, v71
	v_cvt_pk_bf16_f32 v68, v84, v85
	v_cvt_pk_bf16_f32 v69, v82, v83
	global_store_dwordx4 v[72:73], v[66:69], off offset:256
	s_and_saveexec_b64 s[34:35], s[4:5]
	s_cbranch_execz .LBB0_300
	s_waitcnt lgkmcnt(0)
	v_add_f32_e32 v66, v64, v65
	v_lshlrev_b64 v[64:65], 6, v[80:81]
	v_lshl_add_u64 v[64:65], s[8:9], 0, v[64:65]
	v_lshl_add_u64 v[64:65], s[22:23], 2, v[64:65]
	s_lshl_b32 s12, s52, 2
	v_lshl_add_u64 v[64:65], v[64:65], 0, s[12:13]
	global_store_dword v[64:65], v66, off
; __device__ __forceinline__ unsigned cvt_pk_bf16(float lo, float hi) { f32x2_cv v = {lo, hi}; bf16x2_cv b = __builtin_convertvector(v, bf16x2_cv); return __builtin_bit_cast(unsigned, b); }
;     __device__ __forceinline__ void operator()(const f32x4 (&acc)[2][2][4][2], const Unit& u, int wr, int wc, int fr, int fq) const {
;     ...
;         for (int ai = 0; ai < 2; ++ai)
; #pragma unroll
;             for (int m = 0; m < 4; ++m) {
;                 const int row = row0 + ai * HALF + m * 16; const size_t off = (size_t)row * 1024 + col0;
;                 f32x4 b0[2], b1[2];
; #pragma unroll
;                 for (int bj = 0; bj < 2; ++bj) {
;                     if (BASE_BF16) { const u32x4 t = *(const u32x4*)((const bf16_t*)base + off + bj * HALF);
;                         b0[bj] = (f32x4){bf_lo(t.x), bf_hi(t.x), bf_lo(t.y), bf_hi(t.y)}; b1[bj] = (f32x4){bf_lo(t.z), bf_hi(t.z), bf_lo(t.w), bf_hi(t.w)}; }
;                     else { b0[bj] = *(const f32x4*)((const float*)base + off + bj * HALF); b1[bj] = *(const f32x4*)((const float*)base + off + bj * HALF + 4); }
;                 }
;                 float ss = 0.f;
; #pragma unroll
;                 for (int bj = 0; bj < 2; ++bj) {
;                     const f32x4 v0 = b0[bj] + gv[bj][0] * acc[ai][bj][m][0], v1 = b1[bj] + gv[bj][1] * acc[ai][bj][m][1];
;                     if (OUT_BF16) {
;                         u32x4 w; w.x = cvt_pk_bf16(v0[0], v0[1]); w.y = cvt_pk_bf16(v0[2], v0[3]); w.z = cvt_pk_bf16(v1[0], v1[1]); w.w = cvt_pk_bf16(v1[2], v1[3]);
;                         *(u32x4*)((bf16_t*)out + off + bj * HALF) = w;
;                         ss += ((v0[0] * v0[0] + v0[1] * v0[1]) + (v0[2] * v0[2] + v0[3] * v0[3])) + ((v1[0] * v1[0] + v1[1] * v1[1]) + (v1[2] * v1[2] + v1[3] * v1[3]));
;                     } else { *(f32x4*)((float*)out + off + bj * HALF) = v0; *(f32x4*)((float*)out + off + bj * HALF + 4) = v1; }
;                 }
;                 if (OUT_BF16) { ss += __shfl_xor(ss, 16); ss += __shfl_xor(ss, 32); if (fq == 0) rowp[(size_t)row * 16 + u.pn * 4 + wc] = ss; }
;             }
.LBB0_300:
	s_or_b64 exec, exec, s[34:35]
	v_add_u32_e32 v64, 0x80, v154
	s_waitcnt lgkmcnt(0)
	v_ashrrev_i32_e32 v65, 31, v64
	v_lshlrev_b64 v[66:67], 10, v[64:65]
	v_lshl_add_u64 v[82:83], v[66:67], 0, v[144:145]
	v_lshl_add_u64 v[78:79], v[82:83], 2, s[60:61]
	global_load_dwordx4 v[66:69], v[78:79], off nt
	global_load_dwordx4 v[70:73], v[78:79], off offset:16 nt
	global_load_dwordx4 v[74:77], v[78:79], off offset:512 nt
	s_nop 0
	global_load_dwordx4 v[78:81], v[78:79], off offset:528 nt
	s_waitcnt vmcnt(3)
	v_pk_fma_f32 v[62:63], v[62:63], v[162:163], v[68:69]
	v_pk_fma_f32 v[60:61], v[60:61], v[164:165], v[66:67]
	s_waitcnt vmcnt(2)
	v_pk_fma_f32 v[58:59], v[58:59], v[156:157], v[72:73]
	v_pk_fma_f32 v[56:57], v[56:57], v[158:159], v[70:71]
	s_waitcnt vmcnt(1)
	v_pk_fma_f32 v[54:55], v[54:55], v[150:151], v[76:77]
	v_pk_fma_f32 v[52:53], v[52:53], v[152:153], v[74:75]
	s_waitcnt vmcnt(0)
	v_pk_fma_f32 v[66:67], v[50:51], v[146:147], v[80:81]
	v_pk_fma_f32 v[68:69], v[48:49], v[148:149], v[78:79]
	v_cvt_pk_bf16_f32 v48, v60, v61
	v_cvt_pk_bf16_f32 v49, v62, v63
	v_cvt_pk_bf16_f32 v50, v56, v57
	v_mul_f32_e32 v51, v61, v61
	v_mul_f32_e32 v61, v63, v63
	v_mul_f32_e32 v57, v57, v57
	v_mul_f32_e32 v63, v59, v59
	v_mul_f32_e32 v70, v53, v53
	v_mul_f32_e32 v71, v55, v55
	v_mul_f32_e32 v72, v69, v69
	v_mul_f32_e32 v73, v67, v67
	v_fmac_f32_e32 v51, v60, v60
	v_fmac_f32_e32 v61, v62, v62
	v_fmac_f32_e32 v57, v56, v56
	v_fmac_f32_e32 v63, v58, v58
	v_fmac_f32_e32 v70, v52, v52
	v_fmac_f32_e32 v71, v54, v54
	v_fmac_f32_e32 v72, v68, v68
	v_fmac_f32_e32 v73, v66, v66
	v_add_f32_e32 v51, v51, v61
	v_add_f32_e32 v56, v57, v63
	v_add_f32_e32 v57, v70, v71
	v_add_f32_e32 v60, v72, v73
	v_add_f32_e32 v51, v51, v56
	v_add_f32_e32 v56, v57, v60
	v_add_f32_e32 v60, v51, v56
	ds_bpermute_b32 v61, v173, v60
	v_cvt_pk_bf16_f32 v51, v58, v59
	v_lshl_add_u64 v[56:57], v[82:83], 1, s[84:85]
	global_store_dwordx4 v[56:57], v[48:51], off
	s_waitcnt lgkmcnt(0)
	s_nop 0
	v_add_f32_e32 v48, v60, v61
	ds_bpermute_b32 v49, v172, v48
	v_cvt_pk_bf16_f32 v50, v52, v53
	v_cvt_pk_bf16_f32 v51, v54, v55
	v_cvt_pk_bf16_f32 v52, v68, v69
	v_cvt_pk_bf16_f32 v53, v66, v67
	global_store_dwordx4 v[56:57], v[50:53], off offset:256
	s_and_saveexec_b64 s[34:35], s[4:5]
	s_cbranch_execz .LBB0_302
	s_waitcnt lgkmcnt(0)
	v_add_f32_e32 v50, v48, v49
	v_lshlrev_b64 v[48:49], 6, v[64:65]
	v_lshl_add_u64 v[48:49], s[8:9], 0, v[48:49]
	v_lshl_add_u64 v[48:49], s[22:23], 2, v[48:49]
	s_lshl_b32 s12, s52, 2
	v_lshl_add_u64 v[48:49], v[48:49], 0, s[12:13]
	global_store_dword v[48:49], v50, off
.LBB0_302:
	s_or_b64 exec, exec, s[34:35]
	v_add_u32_e32 v48, 0x90, v154
	s_waitcnt lgkmcnt(0)
	v_ashrrev_i32_e32 v49, 31, v48
	v_lshlrev_b64 v[50:51], 10, v[48:49]
	v_lshl_add_u64 v[66:67], v[50:51], 0, v[144:145]
	v_lshl_add_u64 v[62:63], v[66:67], 2, s[60:61]
	global_load_dwordx4 v[50:53], v[62:63], off nt
	global_load_dwordx4 v[54:57], v[62:63], off offset:16 nt
	global_load_dwordx4 v[58:61], v[62:63], off offset:512 nt
	s_nop 0
	global_load_dwordx4 v[62:65], v[62:63], off offset:528 nt
	s_waitcnt vmcnt(3)
	v_pk_fma_f32 v[46:47], v[46:47], v[162:163], v[52:53]
	v_pk_fma_f32 v[44:45], v[44:45], v[164:165], v[50:51]
	s_waitcnt vmcnt(2)
	v_pk_fma_f32 v[42:43], v[42:43], v[156:157], v[56:57]
	v_pk_fma_f32 v[40:41], v[40:41], v[158:159], v[54:55]
	s_waitcnt vmcnt(1)
	v_pk_fma_f32 v[38:39], v[38:39], v[150:151], v[60:61]
	v_pk_fma_f32 v[36:37], v[36:37], v[152:153], v[58:59]
	s_waitcnt vmcnt(0)
	v_pk_fma_f32 v[50:51], v[34:35], v[146:147], v[64:65]
	v_pk_fma_f32 v[52:53], v[32:33], v[148:149], v[62:63]
	v_cvt_pk_bf16_f32 v32, v44, v45
	v_cvt_pk_bf16_f32 v33, v46, v47
	v_cvt_pk_bf16_f32 v34, v40, v41
	v_mul_f32_e32 v35, v45, v45
	v_mul_f32_e32 v45, v47, v47
	v_mul_f32_e32 v41, v41, v41
	v_mul_f32_e32 v47, v43, v43
	v_mul_f32_e32 v54, v37, v37
	v_mul_f32_e32 v55, v39, v39
	v_mul_f32_e32 v56, v53, v53
	v_mul_f32_e32 v57, v51, v51
	v_fmac_f32_e32 v35, v44, v44
	v_fmac_f32_e32 v45, v46, v46
	v_fmac_f32_e32 v41, v40, v40
	v_fmac_f32_e32 v47, v42, v42
	v_fmac_f32_e32 v54, v36, v36
	v_fmac_f32_e32 v55, v38, v38
	v_fmac_f32_e32 v56, v52, v52
	v_fmac_f32_e32 v57, v50, v50
	v_add_f32_e32 v35, v35, v45
	v_add_f32_e32 v40, v41, v47
	v_add_f32_e32 v41, v54, v55
	v_add_f32_e32 v44, v56, v57
	v_add_f32_e32 v35, v35, v40
	v_add_f32_e32 v40, v41, v44
	v_add_f32_e32 v44, v35, v40
	ds_bpermute_b32 v45, v173, v44
	v_cvt_pk_bf16_f32 v35, v42, v43
	v_lshl_add_u64 v[40:41], v[66:67], 1, s[84:85]
	global_store_dwordx4 v[40:41], v[32:35], off
	s_waitcnt lgkmcnt(0)
	s_nop 0
	v_add_f32_e32 v32, v44, v45
	ds_bpermute_b32 v33, v172, v32
	v_cvt_pk_bf16_f32 v34, v36, v37
	v_cvt_pk_bf16_f32 v35, v38, v39
	v_cvt_pk_bf16_f32 v36, v52, v53
	v_cvt_pk_bf16_f32 v37, v50, v51
	global_store_dwordx4 v[40:41], v[34:37], off offset:256
	s_and_saveexec_b64 s[34:35], s[4:5]
	s_cbranch_execz .LBB0_304
	s_waitcnt lgkmcnt(0)
	v_add_f32_e32 v34, v32, v33
	v_lshlrev_b64 v[32:33], 6, v[48:49]
	v_lshl_add_u64 v[32:33], s[8:9], 0, v[32:33]
	v_lshl_add_u64 v[32:33], s[22:23], 2, v[32:33]
	s_lshl_b32 s12, s52, 2
	v_lshl_add_u64 v[32:33], v[32:33], 0, s[12:13]
	global_store_dword v[32:33], v34, off
; __device__ __forceinline__ unsigned cvt_pk_bf16(float lo, float hi) { f32x2_cv v = {lo, hi}; bf16x2_cv b = __builtin_convertvector(v, bf16x2_cv); return __builtin_bit_cast(unsigned, b); }
;     __device__ __forceinline__ void operator()(const f32x4 (&acc)[2][2][4][2], const Unit& u, int wr, int wc, int fr, int fq) const {
;     ...
;         for (int ai = 0; ai < 2; ++ai)
; #pragma unroll
;             for (int m = 0; m < 4; ++m) {
;                 const int row = row0 + ai * HALF + m * 16; const size_t off = (size_t)row * 1024 + col0;
;                 f32x4 b0[2], b1[2];
; #pragma unroll
;                 for (int bj = 0; bj < 2; ++bj) {
;                     if (BASE_BF16) { const u32x4 t = *(const u32x4*)((const bf16_t*)base + off + bj * HALF);
;                         b0[bj] = (f32x4){bf_lo(t.x), bf_hi(t.x), bf_lo(t.y), bf_hi(t.y)}; b1[bj] = (f32x4){bf_lo(t.z), bf_hi(t.z), bf_lo(t.w), bf_hi(t.w)}; }
;                     else { b0[bj] = *(const f32x4*)((const float*)base + off + bj * HALF); b1[bj] = *(const f32x4*)((const float*)base + off + bj * HALF + 4); }
;                 }
;                 float ss = 0.f;
; #pragma unroll
;                 for (int bj = 0; bj < 2; ++bj) {
;                     const f32x4 v0 = b0[bj] + gv[bj][0] * acc[ai][bj][m][0], v1 = b1[bj] + gv[bj][1] * acc[ai][bj][m][1];
;                     if (OUT_BF16) {
;                         u32x4 w; w.x = cvt_pk_bf16(v0[0], v0[1]); w.y = cvt_pk_bf16(v0[2], v0[3]); w.z = cvt_pk_bf16(v1[0], v1[1]); w.w = cvt_pk_bf16(v1[2], v1[3]);
;                         *(u32x4*)((bf16_t*)out + off + bj * HALF) = w;
;                         ss += ((v0[0] * v0[0] + v0[1] * v0[1]) + (v0[2] * v0[2] + v0[3] * v0[3])) + ((v1[0] * v1[0] + v1[1] * v1[1]) + (v1[2] * v1[2] + v1[3] * v1[3]));
;                     } else { *(f32x4*)((float*)out + off + bj * HALF) = v0; *(f32x4*)((float*)out + off + bj * HALF + 4) = v1; }
;                 }
;                 if (OUT_BF16) { ss += __shfl_xor(ss, 16); ss += __shfl_xor(ss, 32); if (fq == 0) rowp[(size_t)row * 16 + u.pn * 4 + wc] = ss; }
;             }
.LBB0_304:
	s_or_b64 exec, exec, s[34:35]
	v_add_u32_e32 v32, 0xa0, v154
	s_waitcnt lgkmcnt(0)
	v_ashrrev_i32_e32 v33, 31, v32
	v_lshlrev_b64 v[34:35], 10, v[32:33]
	v_lshl_add_u64 v[50:51], v[34:35], 0, v[144:145]
	v_lshl_add_u64 v[46:47], v[50:51], 2, s[60:61]
	global_load_dwordx4 v[34:37], v[46:47], off nt
	global_load_dwordx4 v[38:41], v[46:47], off offset:16 nt
	global_load_dwordx4 v[42:45], v[46:47], off offset:512 nt
	s_nop 0
	global_load_dwordx4 v[46:49], v[46:47], off offset:528 nt
	s_waitcnt vmcnt(3)
	v_pk_fma_f32 v[30:31], v[30:31], v[162:163], v[36:37]
	v_pk_fma_f32 v[28:29], v[28:29], v[164:165], v[34:35]
	s_waitcnt vmcnt(2)
	v_pk_fma_f32 v[26:27], v[26:27], v[156:157], v[40:41]
	v_pk_fma_f32 v[24:25], v[24:25], v[158:159], v[38:39]
	s_waitcnt vmcnt(1)
	v_pk_fma_f32 v[22:23], v[22:23], v[150:151], v[44:45]
	v_pk_fma_f32 v[20:21], v[20:21], v[152:153], v[42:43]
	s_waitcnt vmcnt(0)
	v_pk_fma_f32 v[34:35], v[18:19], v[146:147], v[48:49]
	v_pk_fma_f32 v[36:37], v[16:17], v[148:149], v[46:47]
	v_cvt_pk_bf16_f32 v16, v28, v29
	v_cvt_pk_bf16_f32 v17, v30, v31
	v_cvt_pk_bf16_f32 v18, v24, v25
	v_mul_f32_e32 v19, v29, v29
	v_mul_f32_e32 v29, v31, v31
	v_mul_f32_e32 v25, v25, v25
	v_mul_f32_e32 v31, v27, v27
	v_mul_f32_e32 v38, v21, v21
	v_mul_f32_e32 v39, v23, v23
	v_mul_f32_e32 v40, v37, v37
	v_mul_f32_e32 v41, v35, v35
	v_fmac_f32_e32 v19, v28, v28
	v_fmac_f32_e32 v29, v30, v30
	v_fmac_f32_e32 v25, v24, v24
	v_fmac_f32_e32 v31, v26, v26
	v_fmac_f32_e32 v38, v20, v20
	v_fmac_f32_e32 v39, v22, v22
	v_fmac_f32_e32 v40, v36, v36
	v_fmac_f32_e32 v41, v34, v34
	v_add_f32_e32 v19, v19, v29
	v_add_f32_e32 v24, v25, v31
	v_add_f32_e32 v25, v38, v39
	v_add_f32_e32 v28, v40, v41
	v_add_f32_e32 v19, v19, v24
	v_add_f32_e32 v24, v25, v28
	v_add_f32_e32 v28, v19, v24
	ds_bpermute_b32 v29, v173, v28
	v_cvt_pk_bf16_f32 v19, v26, v27
	v_lshl_add_u64 v[24:25], v[50:51], 1, s[84:85]
	global_store_dwordx4 v[24:25], v[16:19], off
	s_waitcnt lgkmcnt(0)
	s_nop 0
	v_add_f32_e32 v16, v28, v29
	ds_bpermute_b32 v17, v172, v16
	v_cvt_pk_bf16_f32 v18, v20, v21
	v_cvt_pk_bf16_f32 v19, v22, v23
	v_cvt_pk_bf16_f32 v20, v36, v37
	v_cvt_pk_bf16_f32 v21, v34, v35
	global_store_dwordx4 v[24:25], v[18:21], off offset:256
	s_and_saveexec_b64 s[34:35], s[4:5]
	s_cbranch_execz .LBB0_306
	s_waitcnt lgkmcnt(0)
	v_add_f32_e32 v18, v16, v17
	v_lshlrev_b64 v[16:17], 6, v[32:33]
	v_lshl_add_u64 v[16:17], s[8:9], 0, v[16:17]
	v_lshl_add_u64 v[16:17], s[22:23], 2, v[16:17]
	s_lshl_b32 s12, s52, 2
	v_lshl_add_u64 v[16:17], v[16:17], 0, s[12:13]
	global_store_dword v[16:17], v18, off
.LBB0_306:
	s_or_b64 exec, exec, s[34:35]
	v_add_u32_e32 v16, 0xb0, v154
	s_waitcnt lgkmcnt(0)
	v_ashrrev_i32_e32 v17, 31, v16
	v_lshlrev_b64 v[18:19], 10, v[16:17]
	v_lshl_add_u64 v[34:35], v[18:19], 0, v[144:145]
	v_lshl_add_u64 v[30:31], v[34:35], 2, s[60:61]
	global_load_dwordx4 v[18:21], v[30:31], off nt
	global_load_dwordx4 v[22:25], v[30:31], off offset:16 nt
	global_load_dwordx4 v[26:29], v[30:31], off offset:512 nt
	s_nop 0
	global_load_dwordx4 v[30:33], v[30:31], off offset:528 nt
	s_waitcnt vmcnt(3)
	v_pk_fma_f32 v[14:15], v[14:15], v[162:163], v[20:21]
	v_pk_fma_f32 v[12:13], v[12:13], v[164:165], v[18:19]
	s_waitcnt vmcnt(2)
	v_pk_fma_f32 v[10:11], v[10:11], v[156:157], v[24:25]
	v_pk_fma_f32 v[8:9], v[8:9], v[158:159], v[22:23]
	s_waitcnt vmcnt(1)
	v_pk_fma_f32 v[6:7], v[6:7], v[150:151], v[28:29]
	v_pk_fma_f32 v[4:5], v[4:5], v[152:153], v[26:27]
	s_waitcnt vmcnt(0)
	v_pk_fma_f32 v[18:19], v[2:3], v[146:147], v[32:33]
	v_pk_fma_f32 v[20:21], v[0:1], v[148:149], v[30:31]
	v_cvt_pk_bf16_f32 v0, v12, v13
	v_cvt_pk_bf16_f32 v1, v14, v15
	v_cvt_pk_bf16_f32 v2, v8, v9
	v_mul_f32_e32 v3, v13, v13
	v_mul_f32_e32 v13, v15, v15
	v_mul_f32_e32 v9, v9, v9
	v_mul_f32_e32 v15, v11, v11
	v_mul_f32_e32 v22, v5, v5
	v_mul_f32_e32 v23, v7, v7
	v_mul_f32_e32 v24, v21, v21
	v_mul_f32_e32 v25, v19, v19
	v_fmac_f32_e32 v3, v12, v12
	v_fmac_f32_e32 v13, v14, v14
	v_fmac_f32_e32 v9, v8, v8
	v_fmac_f32_e32 v15, v10, v10
	v_fmac_f32_e32 v22, v4, v4
	v_fmac_f32_e32 v23, v6, v6
	v_fmac_f32_e32 v24, v20, v20
	v_fmac_f32_e32 v25, v18, v18
	v_add_f32_e32 v3, v3, v13
	v_add_f32_e32 v8, v9, v15
	v_add_f32_e32 v9, v22, v23
	v_add_f32_e32 v12, v24, v25
	v_add_f32_e32 v3, v3, v8
	v_add_f32_e32 v8, v9, v12
	v_add_f32_e32 v12, v3, v8
	ds_bpermute_b32 v13, v173, v12
	v_cvt_pk_bf16_f32 v3, v10, v11
	v_lshl_add_u64 v[8:9], v[34:35], 1, s[84:85]
	global_store_dwordx4 v[8:9], v[0:3], off
	s_waitcnt lgkmcnt(0)
	s_nop 0
	v_add_f32_e32 v0, v12, v13
	ds_bpermute_b32 v1, v172, v0
	v_cvt_pk_bf16_f32 v2, v4, v5
	v_cvt_pk_bf16_f32 v3, v6, v7
	v_cvt_pk_bf16_f32 v4, v20, v21
	v_cvt_pk_bf16_f32 v5, v18, v19
	global_store_dwordx4 v[8:9], v[2:5], off offset:256
	s_and_saveexec_b64 s[34:35], s[4:5]
	s_cbranch_execz .LBB0_308
	s_waitcnt lgkmcnt(0)
	v_add_f32_e32 v2, v0, v1
	v_lshlrev_b64 v[0:1], 6, v[16:17]
	v_lshl_add_u64 v[0:1], s[8:9], 0, v[0:1]
	v_lshl_add_u64 v[0:1], s[22:23], 2, v[0:1]
	s_lshl_b32 s12, s52, 2
	v_lshl_add_u64 v[0:1], v[0:1], 0, s[12:13]
	global_store_dword v[0:1], v2, off

;     __device__ __forceinline__ void operator()(const f32x4 (&acc)[2][2][4][2], const Unit& u, int wr, int wc, int fr, int fq) const {
;         const float* g = gate + (u.pm >> 5) * 9216;
;         const int row0 = u.pm * BM + wr * 64 + fr, col0 = u.pn * BM + wc * 32 + 8 * fq;
;         f32x4 gv[2][2];
; #pragma unroll
;         for (int bj = 0; bj < 2; ++bj)
; #pragma unroll
;             for (int n = 0; n < 2; ++n) gv[bj][n] = *(const f32x4*)(g + col0 + bj * HALF + 4 * n) * coef;
; #pragma unroll
;         for (int ai = 0; ai < 2; ++ai)
; #pragma unroll
;             for (int m = 0; m < 4; ++m) {
;                 const int row = row0 + ai * HALF + m * 16; const size_t off = (size_t)row * 1024 + col0;
;                 f32x4 b0[2], b1[2];
; #pragma unroll
;                 for (int bj = 0; bj < 2; ++bj) {
;                     if (BASE_BF16) { const u32x4 t = *(const u32x4*)((const bf16_t*)base + off + bj * HALF);
;                         b0[bj] = (f32x4){bf_lo(t.x), bf_hi(t.x), bf_lo(t.y), bf_hi(t.y)}; b1[bj] = (f32x4){bf_lo(t.z), bf_hi(t.z), bf_lo(t.w), bf_hi(t.w)}; }
;                     else { b0[bj] = *(const f32x4*)((const float*)base + off + bj * HALF); b1[bj] = *(const f32x4*)((const float*)base + off + bj * HALF + 4); }
;                 }
;                 float ss = 0.f;
; #pragma unroll
;                 for (int bj = 0; bj < 2; ++bj) {
;                     const f32x4 v0 = b0[bj] + gv[bj][0] * acc[ai][bj][m][0], v1 = b1[bj] + gv[bj][1] * acc[ai][bj][m][1];
;                     if (OUT_BF16) {
;                         u32x4 w; w.x = cvt_pk_bf16(v0[0], v0[1]); w.y = cvt_pk_bf16(v0[2], v0[3]); w.z = cvt_pk_bf16(v1[0], v1[1]); w.w = cvt_pk_bf16(v1[2], v1[3]);
;                         *(u32x4*)((bf16_t*)out + off + bj * HALF) = w;
;                         ss += ((v0[0] * v0[0] + v0[1] * v0[1]) + (v0[2] * v0[2] + v0[3] * v0[3])) + ((v1[0] * v1[0] + v1[1] * v1[1]) + (v1[2] * v1[2] + v1[3] * v1[3]));
;                     } else { *(f32x4*)((float*)out + off + bj * HALF) = v0; *(f32x4*)((float*)out + off + bj * HALF + 4) = v1; }
;                 }
;                 if (OUT_BF16) { ss += __shfl_xor(ss, 16); ss += __shfl_xor(ss, 32); if (fq == 0) rowp[(size_t)row * 16 + u.pn * 4 + wc] = ss; }
;             }
.LBB0_811:
	v_lshl_add_u32 v164, s40, 8, v163
	s_lshr_b32 s21, s40, 5
	v_lshl_or_b32 v160, s12, 8, v167
	v_ashrrev_i32_e32 v165, 31, v164
	s_mul_i32 s40, s21, 0x2400
	v_ashrrev_i32_e32 v161, 31, v160
	v_lshlrev_b64 v[80:81], 10, v[164:165]
	s_ashr_i32 s41, s40, 31
	v_lshl_add_u64 v[80:81], v[80:81], 0, v[160:161]
	s_lshl_b64 s[40:41], s[40:41], 2
	v_lshlrev_b64 v[182:183], 1, v[80:81]
	s_add_u32 s40, s54, s40
	v_lshl_add_u64 v[80:81], s[84:85], 0, v[182:183]
	s_addc_u32 s41, s55, s41
	global_load_dwordx4 v[174:177], v[80:81], off nt
	global_load_dwordx4 v[178:181], v[80:81], off offset:256 nt
	v_lshl_add_u64 v[80:81], v[160:161], 2, s[40:41]
	global_load_dwordx4 v[100:103], v[80:81], off nt
	global_load_dwordx4 v[96:99], v[80:81], off offset:16 nt
	global_load_dwordx4 v[84:87], v[80:81], off offset:512 nt
	s_nop 0
	global_load_dwordx4 v[80:83], v[80:81], off offset:528 nt
	v_and_b32_e32 v173, 64, v171
	v_xor_b32_e32 v172, 16, v171
	v_add_u32_e32 v173, 64, v173
	v_xor_b32_e32 v184, 32, v171
	v_cmp_lt_i32_e32 vcc, v172, v173
	s_lshl_b32 s40, s12, 2
	s_ashr_i32 s41, s40, 31
	v_cndmask_b32_e32 v172, v171, v172, vcc
	v_cmp_lt_i32_e32 vcc, v184, v173
	v_lshlrev_b32_e32 v173, 2, v172
	s_waitcnt vmcnt(0)
	v_and_b32_e32 v185, 0xffff0000, v174
	v_cndmask_b32_e32 v184, v171, v184, vcc
	v_lshlrev_b32_e32 v172, 2, v184
	v_lshlrev_b32_e32 v184, 16, v174
	v_lshlrev_b32_e32 v174, 16, v175
	v_and_b32_e32 v175, 0xffff0000, v175
	v_lshlrev_b32_e32 v186, 16, v176
	v_and_b32_e32 v187, 0xffff0000, v176
	v_lshlrev_b32_e32 v176, 16, v177
	v_and_b32_e32 v177, 0xffff0000, v177
	v_lshlrev_b32_e32 v188, 16, v178
	v_and_b32_e32 v189, 0xffff0000, v178
	v_lshlrev_b32_e32 v178, 16, v179
	v_and_b32_e32 v179, 0xffff0000, v179
	v_lshlrev_b32_e32 v190, 16, v180
	v_and_b32_e32 v191, 0xffff0000, v180
	v_lshlrev_b32_e32 v180, 16, v181
	v_and_b32_e32 v181, 0xffff0000, v181
	v_pk_fma_f32 v[142:143], v[142:143], v[102:103], v[174:175]
	v_pk_fma_f32 v[140:141], v[140:141], v[100:101], v[184:185]
	v_pk_fma_f32 v[138:139], v[138:139], v[98:99], v[176:177]
	v_pk_fma_f32 v[136:137], v[136:137], v[96:97], v[186:187]
	v_pk_fma_f32 v[134:135], v[134:135], v[86:87], v[178:179]
	v_pk_fma_f32 v[132:133], v[132:133], v[84:85], v[188:189]
	v_pk_fma_f32 v[174:175], v[130:131], v[82:83], v[180:181]
	v_pk_fma_f32 v[176:177], v[128:129], v[80:81], v[190:191]
	v_cvt_pk_bf16_f32 v128, v140, v141
	v_cvt_pk_bf16_f32 v129, v142, v143
	v_cvt_pk_bf16_f32 v130, v136, v137
	v_mul_f32_e32 v131, v141, v141
	v_mul_f32_e32 v141, v143, v143
	v_mul_f32_e32 v137, v137, v137
	v_mul_f32_e32 v143, v139, v139
	v_mul_f32_e32 v178, v133, v133
	v_mul_f32_e32 v179, v135, v135
	v_mul_f32_e32 v180, v177, v177
	v_mul_f32_e32 v181, v175, v175
	v_fmac_f32_e32 v131, v140, v140
	v_fmac_f32_e32 v141, v142, v142
	v_fmac_f32_e32 v137, v136, v136
	v_fmac_f32_e32 v143, v138, v138
	v_fmac_f32_e32 v178, v132, v132
	v_fmac_f32_e32 v179, v134, v134
	v_fmac_f32_e32 v180, v176, v176
	v_fmac_f32_e32 v181, v174, v174
	v_add_f32_e32 v131, v131, v141
	v_add_f32_e32 v136, v137, v143
	v_add_f32_e32 v137, v178, v179
	v_add_f32_e32 v140, v180, v181
	v_add_f32_e32 v131, v131, v136
	v_add_f32_e32 v136, v137, v140
	v_add_f32_e32 v140, v131, v136
	ds_bpermute_b32 v141, v173, v140
	v_cvt_pk_bf16_f32 v131, v138, v139
	v_lshl_add_u64 v[136:137], s[24:25], 0, v[182:183]
	global_store_dwordx4 v[136:137], v[128:131], off
	s_waitcnt lgkmcnt(0)
	s_nop 0
	v_add_f32_e32 v128, v140, v141
	ds_bpermute_b32 v129, v172, v128
	v_cvt_pk_bf16_f32 v130, v132, v133
	v_cvt_pk_bf16_f32 v131, v134, v135
	v_cvt_pk_bf16_f32 v132, v176, v177
	v_cvt_pk_bf16_f32 v133, v174, v175
	global_store_dwordx4 v[136:137], v[130:133], off offset:256
	s_and_saveexec_b64 s[44:45], s[4:5]
	s_cbranch_execz .LBB0_813
	s_waitcnt lgkmcnt(0)
	v_add_f32_e32 v130, v128, v129
	v_lshlrev_b64 v[128:129], 6, v[164:165]
	v_lshl_add_u64 v[128:129], s[0:1], 0, v[128:129]
	v_lshl_add_u64 v[128:129], s[40:41], 2, v[128:129]
	s_lshl_b32 s12, s56, 2
	v_lshl_add_u64 v[128:129], v[128:129], 0, s[12:13]
	global_store_dword v[128:129], v130, off
.LBB0_813:
	s_or_b64 exec, exec, s[44:45]
	v_or_b32_e32 v128, 16, v164
	s_waitcnt lgkmcnt(0)
	v_ashrrev_i32_e32 v129, 31, v128
	v_lshlrev_b64 v[130:131], 10, v[128:129]
	v_lshl_add_u64 v[130:131], v[130:131], 0, v[160:161]
	v_lshlrev_b64 v[138:139], 1, v[130:131]
	v_lshl_add_u64 v[134:135], s[84:85], 0, v[138:139]
	global_load_dwordx4 v[130:133], v[134:135], off nt
	s_nop 0
	global_load_dwordx4 v[134:137], v[134:135], off offset:256 nt
	s_waitcnt vmcnt(1)
	v_lshlrev_b32_e32 v140, 16, v130
	v_and_b32_e32 v141, 0xffff0000, v130
	v_lshlrev_b32_e32 v130, 16, v131
	v_and_b32_e32 v131, 0xffff0000, v131
	v_lshlrev_b32_e32 v142, 16, v132
	v_and_b32_e32 v143, 0xffff0000, v132
	v_lshlrev_b32_e32 v132, 16, v133
	v_and_b32_e32 v133, 0xffff0000, v133
	s_waitcnt vmcnt(0)
	v_lshlrev_b32_e32 v174, 16, v134
	v_and_b32_e32 v175, 0xffff0000, v134
	v_lshlrev_b32_e32 v134, 16, v135
	v_and_b32_e32 v135, 0xffff0000, v135
	v_lshlrev_b32_e32 v176, 16, v136
	v_and_b32_e32 v177, 0xffff0000, v136
	v_lshlrev_b32_e32 v136, 16, v137
	v_and_b32_e32 v137, 0xffff0000, v137
	v_pk_fma_f32 v[126:127], v[126:127], v[102:103], v[130:131]
	v_pk_fma_f32 v[124:125], v[124:125], v[100:101], v[140:141]
	v_pk_fma_f32 v[122:123], v[122:123], v[98:99], v[132:133]
	v_pk_fma_f32 v[120:121], v[120:121], v[96:97], v[142:143]
	v_pk_fma_f32 v[118:119], v[118:119], v[86:87], v[134:135]
	v_pk_fma_f32 v[116:117], v[116:117], v[84:85], v[174:175]
	v_pk_fma_f32 v[130:131], v[114:115], v[82:83], v[136:137]
	v_pk_fma_f32 v[132:133], v[112:113], v[80:81], v[176:177]
	v_cvt_pk_bf16_f32 v112, v124, v125
	v_cvt_pk_bf16_f32 v113, v126, v127
	v_cvt_pk_bf16_f32 v114, v120, v121
	v_mul_f32_e32 v115, v125, v125
	v_mul_f32_e32 v125, v127, v127
	v_mul_f32_e32 v121, v121, v121
	v_mul_f32_e32 v127, v123, v123
	v_mul_f32_e32 v134, v117, v117
	v_mul_f32_e32 v135, v119, v119
	v_mul_f32_e32 v136, v133, v133
	v_mul_f32_e32 v137, v131, v131
	v_fmac_f32_e32 v115, v124, v124
	v_fmac_f32_e32 v125, v126, v126
	v_fmac_f32_e32 v121, v120, v120
	v_fmac_f32_e32 v127, v122, v122
	v_fmac_f32_e32 v134, v116, v116
	v_fmac_f32_e32 v135, v118, v118
	v_fmac_f32_e32 v136, v132, v132
	v_fmac_f32_e32 v137, v130, v130
	v_add_f32_e32 v115, v115, v125
	v_add_f32_e32 v120, v121, v127
	v_add_f32_e32 v121, v134, v135
	v_add_f32_e32 v124, v136, v137
	v_add_f32_e32 v115, v115, v120
	v_add_f32_e32 v120, v121, v124
	v_add_f32_e32 v124, v115, v120
	ds_bpermute_b32 v125, v173, v124
	v_cvt_pk_bf16_f32 v115, v122, v123
	v_lshl_add_u64 v[120:121], s[24:25], 0, v[138:139]
	global_store_dwordx4 v[120:121], v[112:115], off
	s_waitcnt lgkmcnt(0)
	s_nop 0
	v_add_f32_e32 v112, v124, v125
	ds_bpermute_b32 v113, v172, v112
	v_cvt_pk_bf16_f32 v114, v116, v117
	v_cvt_pk_bf16_f32 v115, v118, v119
	v_cvt_pk_bf16_f32 v116, v132, v133
	v_cvt_pk_bf16_f32 v117, v130, v131
	global_store_dwordx4 v[120:121], v[114:117], off offset:256
	s_and_saveexec_b64 s[44:45], s[4:5]
	s_cbranch_execz .LBB0_815
; __device__ __forceinline__ unsigned cvt_pk_bf16(float lo, float hi) { f32x2_cv v = {lo, hi}; bf16x2_cv b = __builtin_convertvector(v, bf16x2_cv); return __builtin_bit_cast(unsigned, b); }
;     __device__ __forceinline__ void operator()(const f32x4 (&acc)[2][2][4][2], const Unit& u, int wr, int wc, int fr, int fq) const {
;     ...
;         for (int ai = 0; ai < 2; ++ai)
; #pragma unroll
;             for (int m = 0; m < 4; ++m) {
;                 const int row = row0 + ai * HALF + m * 16; const size_t off = (size_t)row * 1024 + col0;
;                 f32x4 b0[2], b1[2];
; #pragma unroll
;                 for (int bj = 0; bj < 2; ++bj) {
;                     if (BASE_BF16) { const u32x4 t = *(const u32x4*)((const bf16_t*)base + off + bj * HALF);
;                         b0[bj] = (f32x4){bf_lo(t.x), bf_hi(t.x), bf_lo(t.y), bf_hi(t.y)}; b1[bj] = (f32x4){bf_lo(t.z), bf_hi(t.z), bf_lo(t.w), bf_hi(t.w)}; }
;                     else { b0[bj] = *(const f32x4*)((const float*)base + off + bj * HALF); b1[bj] = *(const f32x4*)((const float*)base + off + bj * HALF + 4); }
;                 }
;                 float ss = 0.f;
; #pragma unroll
;                 for (int bj = 0; bj < 2; ++bj) {
;                     const f32x4 v0 = b0[bj] + gv[bj][0] * acc[ai][bj][m][0], v1 = b1[bj] + gv[bj][1] * acc[ai][bj][m][1];
;                     if (OUT_BF16) {
;                         u32x4 w; w.x = cvt_pk_bf16(v0[0], v0[1]); w.y = cvt_pk_bf16(v0[2], v0[3]); w.z = cvt_pk_bf16(v1[0], v1[1]); w.w = cvt_pk_bf16(v1[2], v1[3]);
;                         *(u32x4*)((bf16_t*)out + off + bj * HALF) = w;
;                         ss += ((v0[0] * v0[0] + v0[1] * v0[1]) + (v0[2] * v0[2] + v0[3] * v0[3])) + ((v1[0] * v1[0] + v1[1] * v1[1]) + (v1[2] * v1[2] + v1[3] * v1[3]));
;                     } else { *(f32x4*)((float*)out + off + bj * HALF) = v0; *(f32x4*)((float*)out + off + bj * HALF + 4) = v1; }
;                 }
;                 if (OUT_BF16) { ss += __shfl_xor(ss, 16); ss += __shfl_xor(ss, 32); if (fq == 0) rowp[(size_t)row * 16 + u.pn * 4 + wc] = ss; }
;             }
	s_waitcnt lgkmcnt(0)
	v_add_f32_e32 v114, v112, v113
	v_lshlrev_b64 v[112:113], 6, v[128:129]
	v_lshl_add_u64 v[112:113], s[0:1], 0, v[112:113]
	v_lshl_add_u64 v[112:113], s[40:41], 2, v[112:113]
	s_lshl_b32 s12, s56, 2
	v_lshl_add_u64 v[112:113], v[112:113], 0, s[12:13]
	global_store_dword v[112:113], v114, off
.LBB0_815:
	s_or_b64 exec, exec, s[44:45]
	v_or_b32_e32 v112, 32, v164
	s_waitcnt lgkmcnt(0)
	v_ashrrev_i32_e32 v113, 31, v112
	v_lshlrev_b64 v[114:115], 10, v[112:113]
	v_lshl_add_u64 v[114:115], v[114:115], 0, v[160:161]
	v_lshlrev_b64 v[122:123], 1, v[114:115]
	v_lshl_add_u64 v[118:119], s[84:85], 0, v[122:123]
	global_load_dwordx4 v[114:117], v[118:119], off nt
	s_nop 0
	global_load_dwordx4 v[118:121], v[118:119], off offset:256 nt
	s_waitcnt vmcnt(1)
	v_lshlrev_b32_e32 v124, 16, v114
	v_and_b32_e32 v125, 0xffff0000, v114
	v_lshlrev_b32_e32 v114, 16, v115
	v_and_b32_e32 v115, 0xffff0000, v115
	v_lshlrev_b32_e32 v126, 16, v116
	v_and_b32_e32 v127, 0xffff0000, v116
	v_lshlrev_b32_e32 v116, 16, v117
	v_and_b32_e32 v117, 0xffff0000, v117
	s_waitcnt vmcnt(0)
	v_lshlrev_b32_e32 v128, 16, v118
	v_and_b32_e32 v129, 0xffff0000, v118
	v_lshlrev_b32_e32 v118, 16, v119
	v_and_b32_e32 v119, 0xffff0000, v119
	v_lshlrev_b32_e32 v130, 16, v120
	v_and_b32_e32 v131, 0xffff0000, v120
	v_lshlrev_b32_e32 v120, 16, v121
	v_and_b32_e32 v121, 0xffff0000, v121
	v_pk_fma_f32 v[110:111], v[110:111], v[102:103], v[114:115]
	v_pk_fma_f32 v[108:109], v[108:109], v[100:101], v[124:125]
	v_pk_fma_f32 v[106:107], v[106:107], v[98:99], v[116:117]
	v_pk_fma_f32 v[104:105], v[104:105], v[96:97], v[126:127]
	v_pk_fma_f32 v[94:95], v[94:95], v[86:87], v[118:119]
	v_pk_fma_f32 v[92:93], v[92:93], v[84:85], v[128:129]
	v_pk_fma_f32 v[114:115], v[90:91], v[82:83], v[120:121]
	v_pk_fma_f32 v[116:117], v[88:89], v[80:81], v[130:131]
	v_cvt_pk_bf16_f32 v88, v108, v109
	v_cvt_pk_bf16_f32 v89, v110, v111
	v_cvt_pk_bf16_f32 v90, v104, v105
	v_mul_f32_e32 v91, v109, v109
	v_mul_f32_e32 v109, v111, v111
	v_mul_f32_e32 v105, v105, v105
	v_mul_f32_e32 v111, v107, v107
	v_mul_f32_e32 v118, v93, v93
	v_mul_f32_e32 v119, v95, v95
	v_mul_f32_e32 v120, v117, v117
	v_mul_f32_e32 v121, v115, v115
	v_fmac_f32_e32 v91, v108, v108
	v_fmac_f32_e32 v109, v110, v110
	v_fmac_f32_e32 v105, v104, v104
	v_fmac_f32_e32 v111, v106, v106
	v_fmac_f32_e32 v118, v92, v92
	v_fmac_f32_e32 v119, v94, v94
	v_fmac_f32_e32 v120, v116, v116
	v_fmac_f32_e32 v121, v114, v114
	v_add_f32_e32 v91, v91, v109
	v_add_f32_e32 v104, v105, v111
	v_add_f32_e32 v105, v118, v119
	v_add_f32_e32 v108, v120, v121
	v_add_f32_e32 v91, v91, v104
	v_add_f32_e32 v104, v105, v108
	v_add_f32_e32 v108, v91, v104
	ds_bpermute_b32 v109, v173, v108
	v_cvt_pk_bf16_f32 v91, v106, v107
	v_lshl_add_u64 v[104:105], s[24:25], 0, v[122:123]
	global_store_dwordx4 v[104:105], v[88:91], off
	s_waitcnt lgkmcnt(0)
	s_nop 0
	v_add_f32_e32 v88, v108, v109
	ds_bpermute_b32 v89, v172, v88
	v_cvt_pk_bf16_f32 v90, v92, v93
	v_cvt_pk_bf16_f32 v91, v94, v95
	v_cvt_pk_bf16_f32 v92, v116, v117
	v_cvt_pk_bf16_f32 v93, v114, v115
	global_store_dwordx4 v[104:105], v[90:93], off offset:256
	s_and_saveexec_b64 s[44:45], s[4:5]
	s_cbranch_execz .LBB0_817
	s_waitcnt lgkmcnt(0)
	v_add_f32_e32 v90, v88, v89
	v_lshlrev_b64 v[88:89], 6, v[112:113]
	v_lshl_add_u64 v[88:89], s[0:1], 0, v[88:89]
	v_lshl_add_u64 v[88:89], s[40:41], 2, v[88:89]
	s_lshl_b32 s12, s56, 2
	v_lshl_add_u64 v[88:89], v[88:89], 0, s[12:13]
	global_store_dword v[88:89], v90, off
.LBB0_817:
	s_or_b64 exec, exec, s[44:45]
	v_or_b32_e32 v88, 48, v164
	s_waitcnt lgkmcnt(0)
	v_ashrrev_i32_e32 v89, 31, v88
	v_lshlrev_b64 v[90:91], 10, v[88:89]
	v_lshl_add_u64 v[90:91], v[90:91], 0, v[160:161]
	v_lshlrev_b64 v[94:95], 1, v[90:91]
	v_lshl_add_u64 v[104:105], s[84:85], 0, v[94:95]
	global_load_dwordx4 v[90:93], v[104:105], off nt
	s_nop 0
	global_load_dwordx4 v[104:107], v[104:105], off offset:256 nt
	s_waitcnt vmcnt(1)
	v_lshlrev_b32_e32 v108, 16, v90
	v_and_b32_e32 v109, 0xffff0000, v90
	v_lshlrev_b32_e32 v90, 16, v91
	v_and_b32_e32 v91, 0xffff0000, v91
	v_lshlrev_b32_e32 v110, 16, v92
	v_and_b32_e32 v111, 0xffff0000, v92
	v_lshlrev_b32_e32 v92, 16, v93
	v_and_b32_e32 v93, 0xffff0000, v93
	s_waitcnt vmcnt(0)
	v_lshlrev_b32_e32 v112, 16, v104
	v_and_b32_e32 v113, 0xffff0000, v104
	v_lshlrev_b32_e32 v104, 16, v105
	v_and_b32_e32 v105, 0xffff0000, v105
	v_lshlrev_b32_e32 v114, 16, v106
	v_and_b32_e32 v115, 0xffff0000, v106
	v_lshlrev_b32_e32 v106, 16, v107
	v_and_b32_e32 v107, 0xffff0000, v107
	v_pk_fma_f32 v[78:79], v[78:79], v[102:103], v[90:91]
	v_pk_fma_f32 v[76:77], v[76:77], v[100:101], v[108:109]
	v_pk_fma_f32 v[74:75], v[74:75], v[98:99], v[92:93]
	v_pk_fma_f32 v[72:73], v[72:73], v[96:97], v[110:111]
	v_pk_fma_f32 v[70:71], v[70:71], v[86:87], v[104:105]
	v_pk_fma_f32 v[68:69], v[68:69], v[84:85], v[112:113]
	v_pk_fma_f32 v[90:91], v[66:67], v[82:83], v[106:107]
	v_pk_fma_f32 v[92:93], v[64:65], v[80:81], v[114:115]
	v_cvt_pk_bf16_f32 v64, v76, v77
	v_cvt_pk_bf16_f32 v65, v78, v79
	v_cvt_pk_bf16_f32 v66, v72, v73
	v_mul_f32_e32 v67, v77, v77
	v_mul_f32_e32 v77, v79, v79
	v_mul_f32_e32 v73, v73, v73
	v_mul_f32_e32 v79, v75, v75
	v_mul_f32_e32 v104, v69, v69
	v_mul_f32_e32 v105, v71, v71
	v_mul_f32_e32 v106, v93, v93
	v_mul_f32_e32 v107, v91, v91
	v_fmac_f32_e32 v67, v76, v76
	v_fmac_f32_e32 v77, v78, v78
	v_fmac_f32_e32 v73, v72, v72
	v_fmac_f32_e32 v79, v74, v74
	v_fmac_f32_e32 v104, v68, v68
	v_fmac_f32_e32 v105, v70, v70
	v_fmac_f32_e32 v106, v92, v92
	v_fmac_f32_e32 v107, v90, v90
	v_add_f32_e32 v67, v67, v77
	v_add_f32_e32 v72, v73, v79
	v_add_f32_e32 v73, v104, v105
	v_add_f32_e32 v76, v106, v107
	v_add_f32_e32 v67, v67, v72
	v_add_f32_e32 v72, v73, v76
	v_add_f32_e32 v76, v67, v72
	ds_bpermute_b32 v77, v173, v76
	v_cvt_pk_bf16_f32 v67, v74, v75
	v_lshl_add_u64 v[72:73], s[24:25], 0, v[94:95]
	global_store_dwordx4 v[72:73], v[64:67], off
	s_waitcnt lgkmcnt(0)
	s_nop 0
	v_add_f32_e32 v64, v76, v77
	ds_bpermute_b32 v65, v172, v64
	v_cvt_pk_bf16_f32 v66, v68, v69
	v_cvt_pk_bf16_f32 v67, v70, v71
	v_cvt_pk_bf16_f32 v68, v92, v93
	v_cvt_pk_bf16_f32 v69, v90, v91
	global_store_dwordx4 v[72:73], v[66:69], off offset:256
	s_and_saveexec_b64 s[44:45], s[4:5]
	s_cbranch_execz .LBB0_819
	s_waitcnt lgkmcnt(0)
	v_add_f32_e32 v66, v64, v65
	v_lshlrev_b64 v[64:65], 6, v[88:89]
	v_lshl_add_u64 v[64:65], s[0:1], 0, v[64:65]
	v_lshl_add_u64 v[64:65], s[40:41], 2, v[64:65]
	s_lshl_b32 s12, s56, 2
	v_lshl_add_u64 v[64:65], v[64:65], 0, s[12:13]
	global_store_dword v[64:65], v66, off
; __device__ __forceinline__ unsigned cvt_pk_bf16(float lo, float hi) { f32x2_cv v = {lo, hi}; bf16x2_cv b = __builtin_convertvector(v, bf16x2_cv); return __builtin_bit_cast(unsigned, b); }
;     __device__ __forceinline__ void operator()(const f32x4 (&acc)[2][2][4][2], const Unit& u, int wr, int wc, int fr, int fq) const {
;     ...
;         for (int ai = 0; ai < 2; ++ai)
; #pragma unroll
;             for (int m = 0; m < 4; ++m) {
;                 const int row = row0 + ai * HALF + m * 16; const size_t off = (size_t)row * 1024 + col0;
;                 f32x4 b0[2], b1[2];
; #pragma unroll
;                 for (int bj = 0; bj < 2; ++bj) {
;                     if (BASE_BF16) { const u32x4 t = *(const u32x4*)((const bf16_t*)base + off + bj * HALF);
;                         b0[bj] = (f32x4){bf_lo(t.x), bf_hi(t.x), bf_lo(t.y), bf_hi(t.y)}; b1[bj] = (f32x4){bf_lo(t.z), bf_hi(t.z), bf_lo(t.w), bf_hi(t.w)}; }
;                     else { b0[bj] = *(const f32x4*)((const float*)base + off + bj * HALF); b1[bj] = *(const f32x4*)((const float*)base + off + bj * HALF + 4); }
;                 }
;                 float ss = 0.f;
; #pragma unroll
;                 for (int bj = 0; bj < 2; ++bj) {
;                     const f32x4 v0 = b0[bj] + gv[bj][0] * acc[ai][bj][m][0], v1 = b1[bj] + gv[bj][1] * acc[ai][bj][m][1];
;                     if (OUT_BF16) {
;                         u32x4 w; w.x = cvt_pk_bf16(v0[0], v0[1]); w.y = cvt_pk_bf16(v0[2], v0[3]); w.z = cvt_pk_bf16(v1[0], v1[1]); w.w = cvt_pk_bf16(v1[2], v1[3]);
;                         *(u32x4*)((bf16_t*)out + off + bj * HALF) = w;
;                         ss += ((v0[0] * v0[0] + v0[1] * v0[1]) + (v0[2] * v0[2] + v0[3] * v0[3])) + ((v1[0] * v1[0] + v1[1] * v1[1]) + (v1[2] * v1[2] + v1[3] * v1[3]));
;                     } else { *(f32x4*)((float*)out + off + bj * HALF) = v0; *(f32x4*)((float*)out + off + bj * HALF + 4) = v1; }
;                 }
;                 if (OUT_BF16) { ss += __shfl_xor(ss, 16); ss += __shfl_xor(ss, 32); if (fq == 0) rowp[(size_t)row * 16 + u.pn * 4 + wc] = ss; }
;             }
.LBB0_819:
	s_or_b64 exec, exec, s[44:45]
	v_add_u32_e32 v64, 0x80, v164
	s_waitcnt lgkmcnt(0)
	v_ashrrev_i32_e32 v65, 31, v64
	v_lshlrev_b64 v[66:67], 10, v[64:65]
	v_lshl_add_u64 v[66:67], v[66:67], 0, v[160:161]
	v_lshlrev_b64 v[74:75], 1, v[66:67]
	v_lshl_add_u64 v[70:71], s[84:85], 0, v[74:75]
	global_load_dwordx4 v[66:69], v[70:71], off nt
	s_nop 0
	global_load_dwordx4 v[70:73], v[70:71], off offset:256 nt
	s_waitcnt vmcnt(1)
	v_lshlrev_b32_e32 v76, 16, v66
	v_and_b32_e32 v77, 0xffff0000, v66
	v_lshlrev_b32_e32 v66, 16, v67
	v_and_b32_e32 v67, 0xffff0000, v67
	v_lshlrev_b32_e32 v78, 16, v68
	v_and_b32_e32 v79, 0xffff0000, v68
	v_lshlrev_b32_e32 v68, 16, v69
	v_and_b32_e32 v69, 0xffff0000, v69
	s_waitcnt vmcnt(0)
	v_lshlrev_b32_e32 v88, 16, v70
	v_and_b32_e32 v89, 0xffff0000, v70
	v_lshlrev_b32_e32 v70, 16, v71
	v_and_b32_e32 v71, 0xffff0000, v71
	v_lshlrev_b32_e32 v90, 16, v72
	v_and_b32_e32 v91, 0xffff0000, v72
	v_lshlrev_b32_e32 v72, 16, v73
	v_and_b32_e32 v73, 0xffff0000, v73
	v_pk_fma_f32 v[62:63], v[62:63], v[102:103], v[66:67]
	v_pk_fma_f32 v[60:61], v[60:61], v[100:101], v[76:77]
	v_pk_fma_f32 v[58:59], v[58:59], v[98:99], v[68:69]
	v_pk_fma_f32 v[56:57], v[56:57], v[96:97], v[78:79]
	v_pk_fma_f32 v[54:55], v[54:55], v[86:87], v[70:71]
	v_pk_fma_f32 v[52:53], v[52:53], v[84:85], v[88:89]
	v_pk_fma_f32 v[66:67], v[50:51], v[82:83], v[72:73]
	v_pk_fma_f32 v[68:69], v[48:49], v[80:81], v[90:91]
	v_cvt_pk_bf16_f32 v48, v60, v61
	v_cvt_pk_bf16_f32 v49, v62, v63
	v_cvt_pk_bf16_f32 v50, v56, v57
	v_mul_f32_e32 v51, v61, v61
	v_mul_f32_e32 v61, v63, v63
	v_mul_f32_e32 v57, v57, v57
	v_mul_f32_e32 v63, v59, v59
	v_mul_f32_e32 v70, v53, v53
	v_mul_f32_e32 v71, v55, v55
	v_mul_f32_e32 v72, v69, v69
	v_mul_f32_e32 v73, v67, v67
	v_fmac_f32_e32 v51, v60, v60
	v_fmac_f32_e32 v61, v62, v62
	v_fmac_f32_e32 v57, v56, v56
	v_fmac_f32_e32 v63, v58, v58
	v_fmac_f32_e32 v70, v52, v52
	v_fmac_f32_e32 v71, v54, v54
	v_fmac_f32_e32 v72, v68, v68
	v_fmac_f32_e32 v73, v66, v66
	v_add_f32_e32 v51, v51, v61
	v_add_f32_e32 v56, v57, v63
	v_add_f32_e32 v57, v70, v71
	v_add_f32_e32 v60, v72, v73
	v_add_f32_e32 v51, v51, v56
	v_add_f32_e32 v56, v57, v60
	v_add_f32_e32 v60, v51, v56
	ds_bpermute_b32 v61, v173, v60
	v_cvt_pk_bf16_f32 v51, v58, v59
	v_lshl_add_u64 v[56:57], s[24:25], 0, v[74:75]
	global_store_dwordx4 v[56:57], v[48:51], off
	s_waitcnt lgkmcnt(0)
	s_nop 0
	v_add_f32_e32 v48, v60, v61
	ds_bpermute_b32 v49, v172, v48
	v_cvt_pk_bf16_f32 v50, v52, v53
	v_cvt_pk_bf16_f32 v51, v54, v55
	v_cvt_pk_bf16_f32 v52, v68, v69
	v_cvt_pk_bf16_f32 v53, v66, v67
	global_store_dwordx4 v[56:57], v[50:53], off offset:256
	s_and_saveexec_b64 s[44:45], s[4:5]
	s_cbranch_execz .LBB0_821
	s_waitcnt lgkmcnt(0)
	v_add_f32_e32 v50, v48, v49
	v_lshlrev_b64 v[48:49], 6, v[64:65]
	v_lshl_add_u64 v[48:49], s[0:1], 0, v[48:49]
	v_lshl_add_u64 v[48:49], s[40:41], 2, v[48:49]
	s_lshl_b32 s12, s56, 2
	v_lshl_add_u64 v[48:49], v[48:49], 0, s[12:13]
	global_store_dword v[48:49], v50, off
.LBB0_821:
	s_or_b64 exec, exec, s[44:45]
	v_add_u32_e32 v48, 0x90, v164
	s_waitcnt lgkmcnt(0)
	v_ashrrev_i32_e32 v49, 31, v48
	v_lshlrev_b64 v[50:51], 10, v[48:49]
	v_lshl_add_u64 v[50:51], v[50:51], 0, v[160:161]
	v_lshlrev_b64 v[58:59], 1, v[50:51]
	v_lshl_add_u64 v[54:55], s[84:85], 0, v[58:59]
	global_load_dwordx4 v[50:53], v[54:55], off nt
	s_nop 0
	global_load_dwordx4 v[54:57], v[54:55], off offset:256 nt
	s_waitcnt vmcnt(1)
	v_lshlrev_b32_e32 v60, 16, v50
	v_and_b32_e32 v61, 0xffff0000, v50
	v_lshlrev_b32_e32 v50, 16, v51
	v_and_b32_e32 v51, 0xffff0000, v51
	v_lshlrev_b32_e32 v62, 16, v52
	v_and_b32_e32 v63, 0xffff0000, v52
	v_lshlrev_b32_e32 v52, 16, v53
	v_and_b32_e32 v53, 0xffff0000, v53
	s_waitcnt vmcnt(0)
	v_lshlrev_b32_e32 v64, 16, v54
	v_and_b32_e32 v65, 0xffff0000, v54
	v_lshlrev_b32_e32 v54, 16, v55
	v_and_b32_e32 v55, 0xffff0000, v55
	v_lshlrev_b32_e32 v66, 16, v56
	v_and_b32_e32 v67, 0xffff0000, v56
	v_lshlrev_b32_e32 v56, 16, v57
	v_and_b32_e32 v57, 0xffff0000, v57
	v_pk_fma_f32 v[46:47], v[46:47], v[102:103], v[50:51]
	v_pk_fma_f32 v[44:45], v[44:45], v[100:101], v[60:61]
	v_pk_fma_f32 v[42:43], v[42:43], v[98:99], v[52:53]
	v_pk_fma_f32 v[40:41], v[40:41], v[96:97], v[62:63]
	v_pk_fma_f32 v[38:39], v[38:39], v[86:87], v[54:55]
	v_pk_fma_f32 v[36:37], v[36:37], v[84:85], v[64:65]
	v_pk_fma_f32 v[50:51], v[34:35], v[82:83], v[56:57]
	v_pk_fma_f32 v[52:53], v[32:33], v[80:81], v[66:67]
	v_cvt_pk_bf16_f32 v32, v44, v45
	v_cvt_pk_bf16_f32 v33, v46, v47
	v_cvt_pk_bf16_f32 v34, v40, v41
	v_mul_f32_e32 v35, v45, v45
	v_mul_f32_e32 v45, v47, v47
	v_mul_f32_e32 v41, v41, v41
	v_mul_f32_e32 v47, v43, v43
	v_mul_f32_e32 v54, v37, v37
	v_mul_f32_e32 v55, v39, v39
	v_mul_f32_e32 v56, v53, v53
	v_mul_f32_e32 v57, v51, v51
	v_fmac_f32_e32 v35, v44, v44
	v_fmac_f32_e32 v45, v46, v46
	v_fmac_f32_e32 v41, v40, v40
	v_fmac_f32_e32 v47, v42, v42
	v_fmac_f32_e32 v54, v36, v36
	v_fmac_f32_e32 v55, v38, v38
	v_fmac_f32_e32 v56, v52, v52
	v_fmac_f32_e32 v57, v50, v50
	v_add_f32_e32 v35, v35, v45
	v_add_f32_e32 v40, v41, v47
	v_add_f32_e32 v41, v54, v55
	v_add_f32_e32 v44, v56, v57
	v_add_f32_e32 v35, v35, v40
	v_add_f32_e32 v40, v41, v44
	v_add_f32_e32 v44, v35, v40
	ds_bpermute_b32 v45, v173, v44
	v_cvt_pk_bf16_f32 v35, v42, v43
	v_lshl_add_u64 v[40:41], s[24:25], 0, v[58:59]
	global_store_dwordx4 v[40:41], v[32:35], off
	s_waitcnt lgkmcnt(0)
	s_nop 0
	v_add_f32_e32 v32, v44, v45
	ds_bpermute_b32 v33, v172, v32
	v_cvt_pk_bf16_f32 v34, v36, v37
	v_cvt_pk_bf16_f32 v35, v38, v39
	v_cvt_pk_bf16_f32 v36, v52, v53
	v_cvt_pk_bf16_f32 v37, v50, v51
	global_store_dwordx4 v[40:41], v[34:37], off offset:256
	s_and_saveexec_b64 s[44:45], s[4:5]
	s_cbranch_execz .LBB0_823
	s_waitcnt lgkmcnt(0)
	v_add_f32_e32 v34, v32, v33
	v_lshlrev_b64 v[32:33], 6, v[48:49]
	v_lshl_add_u64 v[32:33], s[0:1], 0, v[32:33]
	v_lshl_add_u64 v[32:33], s[40:41], 2, v[32:33]
	s_lshl_b32 s12, s56, 2
	v_lshl_add_u64 v[32:33], v[32:33], 0, s[12:13]
	global_store_dword v[32:33], v34, off
; __device__ __forceinline__ unsigned cvt_pk_bf16(float lo, float hi) { f32x2_cv v = {lo, hi}; bf16x2_cv b = __builtin_convertvector(v, bf16x2_cv); return __builtin_bit_cast(unsigned, b); }
;     __device__ __forceinline__ void operator()(const f32x4 (&acc)[2][2][4][2], const Unit& u, int wr, int wc, int fr, int fq) const {
;     ...
;         for (int ai = 0; ai < 2; ++ai)
; #pragma unroll
;             for (int m = 0; m < 4; ++m) {
;                 const int row = row0 + ai * HALF + m * 16; const size_t off = (size_t)row * 1024 + col0;
;                 f32x4 b0[2], b1[2];
; #pragma unroll
;                 for (int bj = 0; bj < 2; ++bj) {
;                     if (BASE_BF16) { const u32x4 t = *(const u32x4*)((const bf16_t*)base + off + bj * HALF);
;                         b0[bj] = (f32x4){bf_lo(t.x), bf_hi(t.x), bf_lo(t.y), bf_hi(t.y)}; b1[bj] = (f32x4){bf_lo(t.z), bf_hi(t.z), bf_lo(t.w), bf_hi(t.w)}; }
;                     else { b0[bj] = *(const f32x4*)((const float*)base + off + bj * HALF); b1[bj] = *(const f32x4*)((const float*)base + off + bj * HALF + 4); }
;                 }
;                 float ss = 0.f;
; #pragma unroll
;                 for (int bj = 0; bj < 2; ++bj) {
;                     const f32x4 v0 = b0[bj] + gv[bj][0] * acc[ai][bj][m][0], v1 = b1[bj] + gv[bj][1] * acc[ai][bj][m][1];
;                     if (OUT_BF16) {
;                         u32x4 w; w.x = cvt_pk_bf16(v0[0], v0[1]); w.y = cvt_pk_bf16(v0[2], v0[3]); w.z = cvt_pk_bf16(v1[0], v1[1]); w.w = cvt_pk_bf16(v1[2], v1[3]);
;                         *(u32x4*)((bf16_t*)out + off + bj * HALF) = w;
;                         ss += ((v0[0] * v0[0] + v0[1] * v0[1]) + (v0[2] * v0[2] + v0[3] * v0[3])) + ((v1[0] * v1[0] + v1[1] * v1[1]) + (v1[2] * v1[2] + v1[3] * v1[3]));
;                     } else { *(f32x4*)((float*)out + off + bj * HALF) = v0; *(f32x4*)((float*)out + off + bj * HALF + 4) = v1; }
;                 }
;                 if (OUT_BF16) { ss += __shfl_xor(ss, 16); ss += __shfl_xor(ss, 32); if (fq == 0) rowp[(size_t)row * 16 + u.pn * 4 + wc] = ss; }
;             }
.LBB0_823:
	s_or_b64 exec, exec, s[44:45]
	v_add_u32_e32 v32, 0xa0, v164
	s_waitcnt lgkmcnt(0)
	v_ashrrev_i32_e32 v33, 31, v32
	v_lshlrev_b64 v[34:35], 10, v[32:33]
	v_lshl_add_u64 v[34:35], v[34:35], 0, v[160:161]
	v_lshlrev_b64 v[42:43], 1, v[34:35]
	v_lshl_add_u64 v[38:39], s[84:85], 0, v[42:43]
	global_load_dwordx4 v[34:37], v[38:39], off nt
	s_nop 0
	global_load_dwordx4 v[38:41], v[38:39], off offset:256 nt
	s_waitcnt vmcnt(1)
	v_lshlrev_b32_e32 v44, 16, v34
	v_and_b32_e32 v45, 0xffff0000, v34
	v_lshlrev_b32_e32 v34, 16, v35
	v_and_b32_e32 v35, 0xffff0000, v35
	v_lshlrev_b32_e32 v46, 16, v36
	v_and_b32_e32 v47, 0xffff0000, v36
	v_lshlrev_b32_e32 v36, 16, v37
	v_and_b32_e32 v37, 0xffff0000, v37
	s_waitcnt vmcnt(0)
	v_lshlrev_b32_e32 v48, 16, v38
	v_and_b32_e32 v49, 0xffff0000, v38
	v_lshlrev_b32_e32 v38, 16, v39
	v_and_b32_e32 v39, 0xffff0000, v39
	v_lshlrev_b32_e32 v50, 16, v40
	v_and_b32_e32 v51, 0xffff0000, v40
	v_lshlrev_b32_e32 v40, 16, v41
	v_and_b32_e32 v41, 0xffff0000, v41
	v_pk_fma_f32 v[30:31], v[30:31], v[102:103], v[34:35]
	v_pk_fma_f32 v[28:29], v[28:29], v[100:101], v[44:45]
	v_pk_fma_f32 v[26:27], v[26:27], v[98:99], v[36:37]
	v_pk_fma_f32 v[24:25], v[24:25], v[96:97], v[46:47]
	v_pk_fma_f32 v[22:23], v[22:23], v[86:87], v[38:39]
	v_pk_fma_f32 v[20:21], v[20:21], v[84:85], v[48:49]
	v_pk_fma_f32 v[34:35], v[18:19], v[82:83], v[40:41]
	v_pk_fma_f32 v[36:37], v[16:17], v[80:81], v[50:51]
	v_cvt_pk_bf16_f32 v16, v28, v29
	v_cvt_pk_bf16_f32 v17, v30, v31
	v_cvt_pk_bf16_f32 v18, v24, v25
	v_mul_f32_e32 v19, v29, v29
	v_mul_f32_e32 v29, v31, v31
	v_mul_f32_e32 v25, v25, v25
	v_mul_f32_e32 v31, v27, v27
	v_mul_f32_e32 v38, v21, v21
	v_mul_f32_e32 v39, v23, v23
	v_mul_f32_e32 v40, v37, v37
	v_mul_f32_e32 v41, v35, v35
	v_fmac_f32_e32 v19, v28, v28
	v_fmac_f32_e32 v29, v30, v30
	v_fmac_f32_e32 v25, v24, v24
	v_fmac_f32_e32 v31, v26, v26
	v_fmac_f32_e32 v38, v20, v20
	v_fmac_f32_e32 v39, v22, v22
	v_fmac_f32_e32 v40, v36, v36
	v_fmac_f32_e32 v41, v34, v34
	v_add_f32_e32 v19, v19, v29
	v_add_f32_e32 v24, v25, v31
	v_add_f32_e32 v25, v38, v39
	v_add_f32_e32 v28, v40, v41
	v_add_f32_e32 v19, v19, v24
	v_add_f32_e32 v24, v25, v28
	v_add_f32_e32 v28, v19, v24
	ds_bpermute_b32 v29, v173, v28
	v_cvt_pk_bf16_f32 v19, v26, v27
	v_lshl_add_u64 v[24:25], s[24:25], 0, v[42:43]
	global_store_dwordx4 v[24:25], v[16:19], off
	s_waitcnt lgkmcnt(0)
	s_nop 0
	v_add_f32_e32 v16, v28, v29
	ds_bpermute_b32 v17, v172, v16
	v_cvt_pk_bf16_f32 v18, v20, v21
	v_cvt_pk_bf16_f32 v19, v22, v23
	v_cvt_pk_bf16_f32 v20, v36, v37
	v_cvt_pk_bf16_f32 v21, v34, v35
	global_store_dwordx4 v[24:25], v[18:21], off offset:256
	s_and_saveexec_b64 s[44:45], s[4:5]
	s_cbranch_execz .LBB0_825
	s_waitcnt lgkmcnt(0)
	v_add_f32_e32 v18, v16, v17
	v_lshlrev_b64 v[16:17], 6, v[32:33]
	v_lshl_add_u64 v[16:17], s[0:1], 0, v[16:17]
	v_lshl_add_u64 v[16:17], s[40:41], 2, v[16:17]
	s_lshl_b32 s12, s56, 2
	v_lshl_add_u64 v[16:17], v[16:17], 0, s[12:13]
	global_store_dword v[16:17], v18, off
.LBB0_825:
	s_or_b64 exec, exec, s[44:45]
	v_add_u32_e32 v16, 0xb0, v164
	s_waitcnt lgkmcnt(0)
	v_ashrrev_i32_e32 v17, 31, v16
	v_lshlrev_b64 v[18:19], 10, v[16:17]
	v_lshl_add_u64 v[18:19], v[18:19], 0, v[160:161]
	v_lshlrev_b64 v[26:27], 1, v[18:19]
	v_lshl_add_u64 v[22:23], s[84:85], 0, v[26:27]
	global_load_dwordx4 v[18:21], v[22:23], off nt
	s_nop 0
	global_load_dwordx4 v[22:25], v[22:23], off offset:256 nt
	s_waitcnt vmcnt(1)
	v_lshlrev_b32_e32 v28, 16, v18
	v_and_b32_e32 v29, 0xffff0000, v18
	v_lshlrev_b32_e32 v18, 16, v19
	v_and_b32_e32 v19, 0xffff0000, v19
	v_lshlrev_b32_e32 v30, 16, v20
	v_and_b32_e32 v31, 0xffff0000, v20
	v_lshlrev_b32_e32 v20, 16, v21
	v_and_b32_e32 v21, 0xffff0000, v21
	s_waitcnt vmcnt(0)
	v_lshlrev_b32_e32 v32, 16, v22
	v_and_b32_e32 v33, 0xffff0000, v22
	v_lshlrev_b32_e32 v22, 16, v23
	v_and_b32_e32 v23, 0xffff0000, v23
	v_lshlrev_b32_e32 v34, 16, v24
	v_and_b32_e32 v35, 0xffff0000, v24
	v_lshlrev_b32_e32 v24, 16, v25
	v_and_b32_e32 v25, 0xffff0000, v25
	v_pk_fma_f32 v[14:15], v[14:15], v[102:103], v[18:19]
	v_pk_fma_f32 v[12:13], v[12:13], v[100:101], v[28:29]
	v_pk_fma_f32 v[10:11], v[10:11], v[98:99], v[20:21]
	v_pk_fma_f32 v[8:9], v[8:9], v[96:97], v[30:31]
	v_pk_fma_f32 v[6:7], v[6:7], v[86:87], v[22:23]
	v_pk_fma_f32 v[4:5], v[4:5], v[84:85], v[32:33]
	v_pk_fma_f32 v[18:19], v[2:3], v[82:83], v[24:25]
	v_pk_fma_f32 v[20:21], v[0:1], v[80:81], v[34:35]
	v_cvt_pk_bf16_f32 v0, v12, v13
	v_cvt_pk_bf16_f32 v1, v14, v15
	v_cvt_pk_bf16_f32 v2, v8, v9
	v_mul_f32_e32 v3, v13, v13
	v_mul_f32_e32 v13, v15, v15
	v_mul_f32_e32 v9, v9, v9
	v_mul_f32_e32 v15, v11, v11
	v_mul_f32_e32 v22, v5, v5
	v_mul_f32_e32 v23, v7, v7
	v_mul_f32_e32 v24, v21, v21
	v_mul_f32_e32 v25, v19, v19
	v_fmac_f32_e32 v3, v12, v12
	v_fmac_f32_e32 v13, v14, v14
	v_fmac_f32_e32 v9, v8, v8
	v_fmac_f32_e32 v15, v10, v10
	v_fmac_f32_e32 v22, v4, v4
	v_fmac_f32_e32 v23, v6, v6
	v_fmac_f32_e32 v24, v20, v20
	v_fmac_f32_e32 v25, v18, v18
	v_add_f32_e32 v3, v3, v13
	v_add_f32_e32 v8, v9, v15
	v_add_f32_e32 v9, v22, v23
	v_add_f32_e32 v12, v24, v25
	v_add_f32_e32 v3, v3, v8
	v_add_f32_e32 v8, v9, v12
	v_add_f32_e32 v12, v3, v8
	ds_bpermute_b32 v13, v173, v12
	v_cvt_pk_bf16_f32 v3, v10, v11
	v_lshl_add_u64 v[8:9], s[24:25], 0, v[26:27]
	global_store_dwordx4 v[8:9], v[0:3], off
	s_waitcnt lgkmcnt(0)
	s_nop 0
	v_add_f32_e32 v0, v12, v13
	ds_bpermute_b32 v1, v172, v0
	v_cvt_pk_bf16_f32 v2, v4, v5
	v_cvt_pk_bf16_f32 v3, v6, v7
	v_cvt_pk_bf16_f32 v4, v20, v21
	v_cvt_pk_bf16_f32 v5, v18, v19
	global_store_dwordx4 v[8:9], v[2:5], off offset:256
	s_and_saveexec_b64 s[44:45], s[4:5]
	s_cbranch_execz .LBB0_827
	s_waitcnt lgkmcnt(0)
	v_add_f32_e32 v2, v0, v1
	v_lshlrev_b64 v[0:1], 6, v[16:17]
	v_lshl_add_u64 v[0:1], s[0:1], 0, v[0:1]
	v_lshl_add_u64 v[0:1], s[40:41], 2, v[0:1]
	s_lshl_b32 s12, s56, 2
	v_lshl_add_u64 v[0:1], v[0:1], 0, s[12:13]
	global_store_dword v[0:1], v2, off

;     __device__ __forceinline__ void operator()(const f32x4 (&acc)[2][2][4][2], const Unit& u, int wr, int wc, int fr, int fq) const {
;         const float* g = gate + (u.pm >> 5) * 9216;
;         const int row0 = u.pm * BM + wr * 64 + fr, col0 = u.pn * BM + wc * 32 + 8 * fq;
;         f32x4 gv[2][2];
; #pragma unroll
;         for (int bj = 0; bj < 2; ++bj)
; #pragma unroll
;             for (int n = 0; n < 2; ++n) gv[bj][n] = *(const f32x4*)(g + col0 + bj * HALF + 4 * n) * coef;
; #pragma unroll
;         for (int ai = 0; ai < 2; ++ai)
; #pragma unroll
;             for (int m = 0; m < 4; ++m) {
;                 const int row = row0 + ai * HALF + m * 16; const size_t off = (size_t)row * 1024 + col0;
;                 f32x4 b0[2], b1[2];
; #pragma unroll
;                 for (int bj = 0; bj < 2; ++bj) {
;                     if (BASE_BF16) { const u32x4 t = *(const u32x4*)((const bf16_t*)base + off + bj * HALF);
;                         b0[bj] = (f32x4){bf_lo(t.x), bf_hi(t.x), bf_lo(t.y), bf_hi(t.y)}; b1[bj] = (f32x4){bf_lo(t.z), bf_hi(t.z), bf_lo(t.w), bf_hi(t.w)}; }
;                     else { b0[bj] = *(const f32x4*)((const float*)base + off + bj * HALF); b1[bj] = *(const f32x4*)((const float*)base + off + bj * HALF + 4); }
;                 }
;                 float ss = 0.f;
; #pragma unroll
;                 for (int bj = 0; bj < 2; ++bj) {
;                     const f32x4 v0 = b0[bj] + gv[bj][0] * acc[ai][bj][m][0], v1 = b1[bj] + gv[bj][1] * acc[ai][bj][m][1];
;                     if (OUT_BF16) {
;                         u32x4 w; w.x = cvt_pk_bf16(v0[0], v0[1]); w.y = cvt_pk_bf16(v0[2], v0[3]); w.z = cvt_pk_bf16(v1[0], v1[1]); w.w = cvt_pk_bf16(v1[2], v1[3]);
;                         *(u32x4*)((bf16_t*)out + off + bj * HALF) = w;
;                         ss += ((v0[0] * v0[0] + v0[1] * v0[1]) + (v0[2] * v0[2] + v0[3] * v0[3])) + ((v1[0] * v1[0] + v1[1] * v1[1]) + (v1[2] * v1[2] + v1[3] * v1[3]));
;                     } else { *(f32x4*)((float*)out + off + bj * HALF) = v0; *(f32x4*)((float*)out + off + bj * HALF + 4) = v1; }
;                 }
;                 if (OUT_BF16) { ss += __shfl_xor(ss, 16); ss += __shfl_xor(ss, 32); if (fq == 0) rowp[(size_t)row * 16 + u.pn * 4 + wc] = ss; }
;             }
.LBB0_1010:
	s_lshr_b32 s22, s49, 5
	s_mulk_i32 s22, 0x2400
	v_lshl_add_u32 v164, s49, 8, v166
	s_ashr_i32 s23, s22, 31
	v_lshl_or_b32 v162, s50, 8, v168
	v_ashrrev_i32_e32 v165, 31, v164
	s_lshl_b64 s[22:23], s[22:23], 2
	v_ashrrev_i32_e32 v163, 31, v162
	v_lshlrev_b64 v[144:145], 10, v[164:165]
	s_add_u32 s22, s39, s22
	v_lshl_add_u64 v[160:161], v[144:145], 0, v[162:163]
	s_addc_u32 s23, s40, s23
	v_lshl_add_u64 v[148:149], v[160:161], 1, s[24:25]
	v_lshl_add_u64 v[176:177], v[162:163], 2, s[22:23]
	global_load_dwordx4 v[144:147], v[148:149], off nt
	s_nop 0
	global_load_dwordx4 v[148:151], v[148:149], off offset:256 nt
	s_nop 0
	global_load_dwordx4 v[152:155], v[176:177], off nt
	global_load_dwordx4 v[156:159], v[176:177], off offset:16 nt
	global_load_dwordx4 v[172:175], v[176:177], off offset:512 nt
	s_nop 0
	global_load_dwordx4 v[176:179], v[176:177], off offset:528 nt
	v_or_b32_e32 v180, 16, v164
	v_ashrrev_i32_e32 v181, 31, v180
	v_lshlrev_b64 v[180:181], 10, v[180:181]
	v_lshl_add_u64 v[182:183], v[160:161], 2, s[84:85]
	v_lshl_add_u64 v[180:181], v[180:181], 0, v[162:163]
	v_lshl_add_u64 v[184:185], v[180:181], 1, s[24:25]
	s_and_b64 vcc, exec, s[0:1]
	s_mov_b64 s[0:1], -1
	s_waitcnt vmcnt(0)
	v_lshlrev_b32_e32 v186, 16, v144
	v_and_b32_e32 v187, 0xffff0000, v144
	v_lshlrev_b32_e32 v188, 16, v145
	v_and_b32_e32 v189, 0xffff0000, v145
	v_lshlrev_b32_e32 v190, 16, v146
	v_and_b32_e32 v191, 0xffff0000, v146
	v_lshlrev_b32_e32 v192, 16, v147
	v_and_b32_e32 v193, 0xffff0000, v147
	v_pk_mul_f32 v[144:145], v[154:155], 0.5 op_sel_hi:[1,0]
	v_pk_mul_f32 v[146:147], v[152:153], 0.5 op_sel_hi:[1,0]
	v_lshlrev_b32_e32 v194, 16, v148
	v_and_b32_e32 v195, 0xffff0000, v148
	v_lshlrev_b32_e32 v196, 16, v149
	v_and_b32_e32 v197, 0xffff0000, v149
	v_lshlrev_b32_e32 v198, 16, v150
	v_and_b32_e32 v199, 0xffff0000, v150
	v_lshlrev_b32_e32 v200, 16, v151
	v_and_b32_e32 v201, 0xffff0000, v151
	v_pk_mul_f32 v[148:149], v[158:159], 0.5 op_sel_hi:[1,0]
	v_pk_mul_f32 v[150:151], v[156:157], 0.5 op_sel_hi:[1,0]
	v_pk_mul_f32 v[152:153], v[174:175], 0.5 op_sel_hi:[1,0]
	v_pk_mul_f32 v[154:155], v[172:173], 0.5 op_sel_hi:[1,0]
	v_pk_mul_f32 v[156:157], v[178:179], 0.5 op_sel_hi:[1,0]
	v_pk_mul_f32 v[158:159], v[176:177], 0.5 op_sel_hi:[1,0]
	v_pk_fma_f32 v[124:125], v[124:125], v[146:147], v[186:187]
	v_pk_fma_f32 v[126:127], v[126:127], v[144:145], v[188:189]
	v_pk_fma_f32 v[120:121], v[120:121], v[150:151], v[190:191]
	v_pk_fma_f32 v[122:123], v[122:123], v[148:149], v[192:193]
	v_pk_fma_f32 v[116:117], v[116:117], v[154:155], v[194:195]
	v_pk_fma_f32 v[118:119], v[118:119], v[152:153], v[196:197]
	v_pk_fma_f32 v[112:113], v[112:113], v[158:159], v[198:199]
	v_pk_fma_f32 v[114:115], v[114:115], v[156:157], v[200:201]
	global_store_dwordx4 v[182:183], v[124:127], off nt
	global_store_dwordx4 v[182:183], v[120:123], off offset:16 nt
	global_store_dwordx4 v[182:183], v[116:119], off offset:512 nt
	global_store_dwordx4 v[182:183], v[112:115], off offset:528 nt
	global_load_dwordx4 v[112:115], v[184:185], off nt
	s_nop 0
	global_load_dwordx4 v[116:119], v[184:185], off offset:256 nt
	v_or_b32_e32 v120, 32, v164
	v_ashrrev_i32_e32 v121, 31, v120
	v_lshlrev_b64 v[120:121], 10, v[120:121]
	v_lshl_add_u64 v[120:121], v[120:121], 0, v[162:163]
	v_lshl_add_u64 v[122:123], v[180:181], 2, s[84:85]
	v_lshl_add_u64 v[124:125], v[120:121], 1, s[24:25]
	s_waitcnt vmcnt(1)
	v_lshlrev_b32_e32 v126, 16, v112
	v_and_b32_e32 v127, 0xffff0000, v112
	v_lshlrev_b32_e32 v112, 16, v113
	v_and_b32_e32 v113, 0xffff0000, v113
	v_lshlrev_b32_e32 v172, 16, v114
	v_and_b32_e32 v173, 0xffff0000, v114
	v_lshlrev_b32_e32 v114, 16, v115
	v_and_b32_e32 v115, 0xffff0000, v115
	s_waitcnt vmcnt(0)
	v_lshlrev_b32_e32 v174, 16, v116
	v_and_b32_e32 v175, 0xffff0000, v116
	v_lshlrev_b32_e32 v116, 16, v117
	v_and_b32_e32 v117, 0xffff0000, v117
	v_lshlrev_b32_e32 v176, 16, v118
	v_and_b32_e32 v177, 0xffff0000, v118
	v_lshlrev_b32_e32 v118, 16, v119
	v_and_b32_e32 v119, 0xffff0000, v119
	v_pk_fma_f32 v[110:111], v[110:111], v[144:145], v[112:113]
	v_pk_fma_f32 v[108:109], v[108:109], v[146:147], v[126:127]
	v_pk_fma_f32 v[106:107], v[106:107], v[148:149], v[114:115]
	v_pk_fma_f32 v[104:105], v[104:105], v[150:151], v[172:173]
	v_pk_fma_f32 v[102:103], v[102:103], v[152:153], v[116:117]
	v_pk_fma_f32 v[100:101], v[100:101], v[154:155], v[174:175]
	v_pk_fma_f32 v[98:99], v[98:99], v[156:157], v[118:119]
	v_pk_fma_f32 v[96:97], v[96:97], v[158:159], v[176:177]
	global_store_dwordx4 v[122:123], v[108:111], off nt
	global_store_dwordx4 v[122:123], v[104:107], off offset:16 nt
	global_store_dwordx4 v[122:123], v[100:103], off offset:512 nt
	global_store_dwordx4 v[122:123], v[96:99], off offset:528 nt
	global_load_dwordx4 v[96:99], v[124:125], off nt
	s_nop 0
	global_load_dwordx4 v[100:103], v[124:125], off offset:256 nt
	v_or_b32_e32 v104, 48, v164
	v_ashrrev_i32_e32 v105, 31, v104
	v_lshlrev_b64 v[104:105], 10, v[104:105]
	v_lshl_add_u64 v[104:105], v[104:105], 0, v[162:163]
	v_lshl_add_u64 v[106:107], v[120:121], 2, s[84:85]
	v_lshl_add_u64 v[108:109], v[104:105], 1, s[24:25]
	s_waitcnt vmcnt(1)
	v_lshlrev_b32_e32 v110, 16, v96
	v_and_b32_e32 v111, 0xffff0000, v96
	v_lshlrev_b32_e32 v96, 16, v97
	v_and_b32_e32 v97, 0xffff0000, v97
	v_lshlrev_b32_e32 v112, 16, v98
	v_and_b32_e32 v113, 0xffff0000, v98
	v_lshlrev_b32_e32 v98, 16, v99
	v_and_b32_e32 v99, 0xffff0000, v99
	s_waitcnt vmcnt(0)
; __device__ __forceinline__ unsigned cvt_pk_bf16(float lo, float hi) { f32x2_cv v = {lo, hi}; bf16x2_cv b = __builtin_convertvector(v, bf16x2_cv); return __builtin_bit_cast(unsigned, b); }
;     __device__ __forceinline__ void operator()(const f32x4 (&acc)[2][2][4][2], const Unit& u, int wr, int wc, int fr, int fq) const {
;     ...
;         for (int ai = 0; ai < 2; ++ai)
; #pragma unroll
;             for (int m = 0; m < 4; ++m) {
;                 const int row = row0 + ai * HALF + m * 16; const size_t off = (size_t)row * 1024 + col0;
;                 f32x4 b0[2], b1[2];
; #pragma unroll
;                 for (int bj = 0; bj < 2; ++bj) {
;                     if (BASE_BF16) { const u32x4 t = *(const u32x4*)((const bf16_t*)base + off + bj * HALF);
;                         b0[bj] = (f32x4){bf_lo(t.x), bf_hi(t.x), bf_lo(t.y), bf_hi(t.y)}; b1[bj] = (f32x4){bf_lo(t.z), bf_hi(t.z), bf_lo(t.w), bf_hi(t.w)}; }
;                     else { b0[bj] = *(const f32x4*)((const float*)base + off + bj * HALF); b1[bj] = *(const f32x4*)((const float*)base + off + bj * HALF + 4); }
;                 }
;                 float ss = 0.f;
; #pragma unroll
;                 for (int bj = 0; bj < 2; ++bj) {
;                     const f32x4 v0 = b0[bj] + gv[bj][0] * acc[ai][bj][m][0], v1 = b1[bj] + gv[bj][1] * acc[ai][bj][m][1];
;                     if (OUT_BF16) {
;                         u32x4 w; w.x = cvt_pk_bf16(v0[0], v0[1]); w.y = cvt_pk_bf16(v0[2], v0[3]); w.z = cvt_pk_bf16(v1[0], v1[1]); w.w = cvt_pk_bf16(v1[2], v1[3]);
;                         *(u32x4*)((bf16_t*)out + off + bj * HALF) = w;
;                         ss += ((v0[0] * v0[0] + v0[1] * v0[1]) + (v0[2] * v0[2] + v0[3] * v0[3])) + ((v1[0] * v1[0] + v1[1] * v1[1]) + (v1[2] * v1[2] + v1[3] * v1[3]));
;                     } else { *(f32x4*)((float*)out + off + bj * HALF) = v0; *(f32x4*)((float*)out + off + bj * HALF + 4) = v1; }
;                 }
;                 if (OUT_BF16) { ss += __shfl_xor(ss, 16); ss += __shfl_xor(ss, 32); if (fq == 0) rowp[(size_t)row * 16 + u.pn * 4 + wc] = ss; }
;             }
	v_lshlrev_b32_e32 v114, 16, v100
	v_and_b32_e32 v115, 0xffff0000, v100
	v_lshlrev_b32_e32 v100, 16, v101
	v_and_b32_e32 v101, 0xffff0000, v101
	v_lshlrev_b32_e32 v116, 16, v102
	v_and_b32_e32 v117, 0xffff0000, v102
	v_lshlrev_b32_e32 v102, 16, v103
	v_and_b32_e32 v103, 0xffff0000, v103
	v_pk_fma_f32 v[94:95], v[94:95], v[144:145], v[96:97]
	v_pk_fma_f32 v[92:93], v[92:93], v[146:147], v[110:111]
	v_pk_fma_f32 v[90:91], v[90:91], v[148:149], v[98:99]
	v_pk_fma_f32 v[88:89], v[88:89], v[150:151], v[112:113]
	v_pk_fma_f32 v[86:87], v[86:87], v[152:153], v[100:101]
	v_pk_fma_f32 v[84:85], v[84:85], v[154:155], v[114:115]
	v_pk_fma_f32 v[82:83], v[82:83], v[156:157], v[102:103]
	v_pk_fma_f32 v[80:81], v[80:81], v[158:159], v[116:117]
	global_store_dwordx4 v[106:107], v[92:95], off nt
	global_store_dwordx4 v[106:107], v[88:91], off offset:16 nt
	global_store_dwordx4 v[106:107], v[84:87], off offset:512 nt
	global_store_dwordx4 v[106:107], v[80:83], off offset:528 nt
	global_load_dwordx4 v[80:83], v[108:109], off nt
	s_nop 0
	global_load_dwordx4 v[84:87], v[108:109], off offset:256 nt
	v_lshl_add_u64 v[88:89], v[160:161], 0, s[12:13]
	v_lshl_add_u64 v[90:91], v[104:105], 2, s[84:85]
	v_lshl_add_u64 v[92:93], v[88:89], 1, s[24:25]
	s_waitcnt vmcnt(1)
	v_lshlrev_b32_e32 v94, 16, v80
	v_and_b32_e32 v95, 0xffff0000, v80
	v_lshlrev_b32_e32 v80, 16, v81
	v_and_b32_e32 v81, 0xffff0000, v81
	v_lshlrev_b32_e32 v96, 16, v82
	v_and_b32_e32 v97, 0xffff0000, v82
	v_lshlrev_b32_e32 v82, 16, v83
	v_and_b32_e32 v83, 0xffff0000, v83
	s_waitcnt vmcnt(0)
	v_lshlrev_b32_e32 v98, 16, v84
	v_and_b32_e32 v99, 0xffff0000, v84
	v_lshlrev_b32_e32 v84, 16, v85
	v_and_b32_e32 v85, 0xffff0000, v85
	v_lshlrev_b32_e32 v100, 16, v86
	v_and_b32_e32 v101, 0xffff0000, v86
	v_lshlrev_b32_e32 v86, 16, v87
	v_and_b32_e32 v87, 0xffff0000, v87
	v_pk_fma_f32 v[78:79], v[78:79], v[144:145], v[80:81]
	v_pk_fma_f32 v[76:77], v[76:77], v[146:147], v[94:95]
	v_pk_fma_f32 v[74:75], v[74:75], v[148:149], v[82:83]
	v_pk_fma_f32 v[72:73], v[72:73], v[150:151], v[96:97]
	v_pk_fma_f32 v[70:71], v[70:71], v[152:153], v[84:85]
	v_pk_fma_f32 v[68:69], v[68:69], v[154:155], v[98:99]
	v_pk_fma_f32 v[66:67], v[66:67], v[156:157], v[86:87]
	v_pk_fma_f32 v[64:65], v[64:65], v[158:159], v[100:101]
	global_store_dwordx4 v[90:91], v[76:79], off nt
	global_store_dwordx4 v[90:91], v[72:75], off offset:16 nt
	global_store_dwordx4 v[90:91], v[68:71], off offset:512 nt
	global_store_dwordx4 v[90:91], v[64:67], off offset:528 nt
	global_load_dwordx4 v[64:67], v[92:93], off nt
	s_nop 0
	global_load_dwordx4 v[68:71], v[92:93], off offset:256 nt
	v_lshl_add_u64 v[72:73], v[160:161], 0, s[14:15]
	v_lshl_add_u64 v[74:75], v[88:89], 2, s[84:85]
	v_lshl_add_u64 v[76:77], v[72:73], 1, s[24:25]
	s_waitcnt vmcnt(1)
	v_lshlrev_b32_e32 v78, 16, v64
	v_and_b32_e32 v79, 0xffff0000, v64
	v_lshlrev_b32_e32 v64, 16, v65
	v_and_b32_e32 v65, 0xffff0000, v65
	v_lshlrev_b32_e32 v80, 16, v66
	v_and_b32_e32 v81, 0xffff0000, v66
	v_lshlrev_b32_e32 v66, 16, v67
	v_and_b32_e32 v67, 0xffff0000, v67
	s_waitcnt vmcnt(0)
	v_lshlrev_b32_e32 v82, 16, v68
	v_and_b32_e32 v83, 0xffff0000, v68
	v_lshlrev_b32_e32 v68, 16, v69
	v_and_b32_e32 v69, 0xffff0000, v69
	v_lshlrev_b32_e32 v84, 16, v70
	v_and_b32_e32 v85, 0xffff0000, v70
	v_lshlrev_b32_e32 v70, 16, v71
	v_and_b32_e32 v71, 0xffff0000, v71
	v_pk_fma_f32 v[62:63], v[62:63], v[144:145], v[64:65]
	v_pk_fma_f32 v[60:61], v[60:61], v[146:147], v[78:79]
	v_pk_fma_f32 v[58:59], v[58:59], v[148:149], v[66:67]
	v_pk_fma_f32 v[56:57], v[56:57], v[150:151], v[80:81]
	v_pk_fma_f32 v[54:55], v[54:55], v[152:153], v[68:69]
	v_pk_fma_f32 v[52:53], v[52:53], v[154:155], v[82:83]
	v_pk_fma_f32 v[50:51], v[50:51], v[156:157], v[70:71]
	v_pk_fma_f32 v[48:49], v[48:49], v[158:159], v[84:85]
	global_store_dwordx4 v[74:75], v[60:63], off nt
	global_store_dwordx4 v[74:75], v[56:59], off offset:16 nt
	global_store_dwordx4 v[74:75], v[52:55], off offset:512 nt
	global_store_dwordx4 v[74:75], v[48:51], off offset:528 nt
	global_load_dwordx4 v[48:51], v[76:77], off nt
	s_nop 0
	global_load_dwordx4 v[52:55], v[76:77], off offset:256 nt
	v_lshl_add_u64 v[56:57], v[160:161], 0, s[16:17]
	v_lshl_add_u64 v[58:59], v[72:73], 2, s[84:85]
	v_lshl_add_u64 v[60:61], v[56:57], 1, s[24:25]
	s_waitcnt vmcnt(1)
; template <class Epi, class Sched, bool ALIGN_EPI = false, bool SP2 = false>
; __device__ __forceinline__ void gemm_phase(PG8_LAS unsigned char* lds, const Gemm g, const Sched& S, const Epi& E) {
;     ...
;         if constexpr (ALIGN_EPI) { if (wr == 0) PG8_BAR; }
;         if constexpr (!Epi::AFTER_DRAIN) { E(acc, cur, wr, wc, fr, fq); S.done(cur); }
;         if (!has_next) break;
;         if constexpr (!Epi::CHAIN) {
; #pragma unroll
;         for (int a = 0; a < 2; ++a)
; #pragma unroll
;     __device__ __forceinline__ void operator()(const f32x4 (&acc)[2][2][4][2], const Unit& u, int wr, int wc, int fr, int fq) const {
;     ...
;         for (int ai = 0; ai < 2; ++ai)
; #pragma unroll
;             for (int m = 0; m < 4; ++m) {
;                 const int row = row0 + ai * HALF + m * 16; const size_t off = (size_t)row * 1024 + col0;
;                 f32x4 b0[2], b1[2];
; #pragma unroll
;                 for (int bj = 0; bj < 2; ++bj) {
;                     if (BASE_BF16) { const u32x4 t = *(const u32x4*)((const bf16_t*)base + off + bj * HALF);
;                         b0[bj] = (f32x4){bf_lo(t.x), bf_hi(t.x), bf_lo(t.y), bf_hi(t.y)}; b1[bj] = (f32x4){bf_lo(t.z), bf_hi(t.z), bf_lo(t.w), bf_hi(t.w)}; }
;                     else { b0[bj] = *(const f32x4*)((const float*)base + off + bj * HALF); b1[bj] = *(const f32x4*)((const float*)base + off + bj * HALF + 4); }
;                 }
;                 float ss = 0.f;
; #pragma unroll
;                 for (int bj = 0; bj < 2; ++bj) {
;                     const f32x4 v0 = b0[bj] + gv[bj][0] * acc[ai][bj][m][0], v1 = b1[bj] + gv[bj][1] * acc[ai][bj][m][1];
;                     if (OUT_BF16) {
;                         u32x4 w; w.x = cvt_pk_bf16(v0[0], v0[1]); w.y = cvt_pk_bf16(v0[2], v0[3]); w.z = cvt_pk_bf16(v1[0], v1[1]); w.w = cvt_pk_bf16(v1[2], v1[3]);
;                         *(u32x4*)((bf16_t*)out + off + bj * HALF) = w;
;                         ss += ((v0[0] * v0[0] + v0[1] * v0[1]) + (v0[2] * v0[2] + v0[3] * v0[3])) + ((v1[0] * v1[0] + v1[1] * v1[1]) + (v1[2] * v1[2] + v1[3] * v1[3]));
;                     } else { *(f32x4*)((float*)out + off + bj * HALF) = v0; *(f32x4*)((float*)out + off + bj * HALF + 4) = v1; }
;                 }
;                 if (OUT_BF16) { ss += __shfl_xor(ss, 16); ss += __shfl_xor(ss, 32); if (fq == 0) rowp[(size_t)row * 16 + u.pn * 4 + wc] = ss; }
;             }
	v_lshlrev_b32_e32 v62, 16, v48
	v_and_b32_e32 v63, 0xffff0000, v48
	v_lshlrev_b32_e32 v48, 16, v49
	v_and_b32_e32 v49, 0xffff0000, v49
	v_lshlrev_b32_e32 v64, 16, v50
	v_and_b32_e32 v65, 0xffff0000, v50
	v_lshlrev_b32_e32 v50, 16, v51
	v_and_b32_e32 v51, 0xffff0000, v51
	s_waitcnt vmcnt(0)
	v_lshlrev_b32_e32 v66, 16, v52
	v_and_b32_e32 v67, 0xffff0000, v52
	v_lshlrev_b32_e32 v52, 16, v53
	v_and_b32_e32 v53, 0xffff0000, v53
	v_lshlrev_b32_e32 v68, 16, v54
	v_and_b32_e32 v69, 0xffff0000, v54
	v_lshlrev_b32_e32 v54, 16, v55
	v_and_b32_e32 v55, 0xffff0000, v55
	v_pk_fma_f32 v[46:47], v[46:47], v[144:145], v[48:49]
	v_pk_fma_f32 v[44:45], v[44:45], v[146:147], v[62:63]
	v_pk_fma_f32 v[42:43], v[42:43], v[148:149], v[50:51]
	v_pk_fma_f32 v[40:41], v[40:41], v[150:151], v[64:65]
	v_pk_fma_f32 v[38:39], v[38:39], v[152:153], v[52:53]
	v_pk_fma_f32 v[36:37], v[36:37], v[154:155], v[66:67]
	v_pk_fma_f32 v[34:35], v[34:35], v[156:157], v[54:55]
	v_pk_fma_f32 v[32:33], v[32:33], v[158:159], v[68:69]
	global_store_dwordx4 v[58:59], v[44:47], off nt
	global_store_dwordx4 v[58:59], v[40:43], off offset:16 nt
	global_store_dwordx4 v[58:59], v[36:39], off offset:512 nt
	global_store_dwordx4 v[58:59], v[32:35], off offset:528 nt
	global_load_dwordx4 v[32:35], v[60:61], off nt
	s_nop 0
	global_load_dwordx4 v[36:39], v[60:61], off offset:256 nt
	v_lshl_add_u64 v[40:41], v[160:161], 0, s[18:19]
	v_lshl_add_u64 v[42:43], v[56:57], 2, s[84:85]
	v_lshl_add_u64 v[44:45], v[40:41], 1, s[24:25]
	s_waitcnt vmcnt(1)
	v_lshlrev_b32_e32 v46, 16, v32
	v_and_b32_e32 v47, 0xffff0000, v32
	v_lshlrev_b32_e32 v32, 16, v33
	v_and_b32_e32 v33, 0xffff0000, v33
	v_lshlrev_b32_e32 v48, 16, v34
	v_and_b32_e32 v49, 0xffff0000, v34
	v_lshlrev_b32_e32 v34, 16, v35
	v_and_b32_e32 v35, 0xffff0000, v35
	s_waitcnt vmcnt(0)
	v_lshlrev_b32_e32 v50, 16, v36
	v_and_b32_e32 v51, 0xffff0000, v36
	v_lshlrev_b32_e32 v36, 16, v37
	v_and_b32_e32 v37, 0xffff0000, v37
	v_lshlrev_b32_e32 v52, 16, v38
	v_and_b32_e32 v53, 0xffff0000, v38
	v_lshlrev_b32_e32 v38, 16, v39
	v_and_b32_e32 v39, 0xffff0000, v39
	v_pk_fma_f32 v[30:31], v[30:31], v[144:145], v[32:33]
	v_pk_fma_f32 v[28:29], v[28:29], v[146:147], v[46:47]
	v_pk_fma_f32 v[26:27], v[26:27], v[148:149], v[34:35]
	v_pk_fma_f32 v[24:25], v[24:25], v[150:151], v[48:49]
	v_pk_fma_f32 v[22:23], v[22:23], v[152:153], v[36:37]
	v_pk_fma_f32 v[20:21], v[20:21], v[154:155], v[50:51]
	v_pk_fma_f32 v[18:19], v[18:19], v[156:157], v[38:39]
	v_pk_fma_f32 v[16:17], v[16:17], v[158:159], v[52:53]
	global_store_dwordx4 v[42:43], v[28:31], off nt
	global_store_dwordx4 v[42:43], v[24:27], off offset:16 nt
	global_store_dwordx4 v[42:43], v[20:23], off offset:512 nt
	global_store_dwordx4 v[42:43], v[16:19], off offset:528 nt
	global_load_dwordx4 v[16:19], v[44:45], off nt
	s_nop 0
	global_load_dwordx4 v[20:23], v[44:45], off offset:256 nt
	v_lshl_add_u64 v[24:25], v[40:41], 2, s[84:85]
	s_waitcnt vmcnt(1)
	v_lshlrev_b32_e32 v26, 16, v16
	v_and_b32_e32 v27, 0xffff0000, v16
	v_lshlrev_b32_e32 v16, 16, v17
	v_and_b32_e32 v17, 0xffff0000, v17
	v_lshlrev_b32_e32 v28, 16, v18
	v_and_b32_e32 v29, 0xffff0000, v18
	v_lshlrev_b32_e32 v18, 16, v19
	v_and_b32_e32 v19, 0xffff0000, v19
	s_waitcnt vmcnt(0)
	v_lshlrev_b32_e32 v30, 16, v20
	v_and_b32_e32 v31, 0xffff0000, v20
	v_lshlrev_b32_e32 v20, 16, v21
	v_and_b32_e32 v21, 0xffff0000, v21
	v_lshlrev_b32_e32 v32, 16, v22
	v_and_b32_e32 v33, 0xffff0000, v22
	v_lshlrev_b32_e32 v22, 16, v23
	v_and_b32_e32 v23, 0xffff0000, v23
	v_pk_fma_f32 v[14:15], v[14:15], v[144:145], v[16:17]
	v_pk_fma_f32 v[12:13], v[12:13], v[146:147], v[26:27]
	v_pk_fma_f32 v[10:11], v[10:11], v[148:149], v[18:19]
	v_pk_fma_f32 v[8:9], v[8:9], v[150:151], v[28:29]
	v_pk_fma_f32 v[6:7], v[6:7], v[152:153], v[20:21]
	v_pk_fma_f32 v[4:5], v[4:5], v[154:155], v[30:31]
	v_pk_fma_f32 v[2:3], v[2:3], v[156:157], v[22:23]
	v_pk_fma_f32 v[0:1], v[0:1], v[158:159], v[32:33]
	global_store_dwordx4 v[24:25], v[12:15], off nt
	global_store_dwordx4 v[24:25], v[8:11], off offset:16 nt
	global_store_dwordx4 v[24:25], v[4:7], off offset:512 nt
	global_store_dwordx4 v[24:25], v[0:3], off offset:528 nt
	s_cbranch_vccnz .LBB0_995
	s_andn2_b64 vcc, exec, s[6:7]
	s_cbranch_vccnz .LBB0_994
	s_barrier
	s_branch .LBB0_994
